# attention unit rewritten on v_mfma_f32_16x16x32_bf16 (S^T/O^T as 16x16 tiles, K LDS swizzle changed, O converted to 32x32 layout at exit)
# speedup vs baseline: 1.0191x; 1.0107x over previous
; __device__ __forceinline__ void attn_unit(unsigned char* ws, const float* sub_g, LAS unsigned char* lds, int h, int qb, float negM, float lam) {
;     const int tid = threadIdx.x, lane = tid & 63, r32 = lane & 31, hi = lane >> 5;
;     const int wid = __builtin_amdgcn_readfirstlane(tid >> 6), map = wid >> 2, wq = wid & 3;
;     const int qrow0 = qb * 128 + 32 * wq;
;     const bf16_t* Qp = (const bf16_t*)(ws + WS_Q); const bf16_t* Kp = (const bf16_t*)(ws + WS_K); const bf16_t* VTp = (const bf16_t*)(ws + WS_VT);
;     bf16x8 qf[4];
;     {
;         const bf16_t* qp = Qp + (size_t)(qrow0 + r32) * 1024 + (h * 2 + map) * 64 + 8 * hi;
; #pragma unroll
;         for (int d0 = 0; d0 < 4; ++d0) qf[d0] = *(const bf16x8*)(qp + 16 * d0);
;     }
;     const bf16_t* kg[2]; const bf16_t* vg[2];
; #pragma unroll
;     for (int i = 0; i < 2; ++i) {
;         const int g = 2 * wid + i;
;         const int kr = 4 * g + (lane >> 4), kc = (lane & 15) ^ (kr & 15);
;         kg[i] = Kp + (size_t)kr * 1024 + h * 128 + kc * 8;
;         const int vr = 8 * g + (lane >> 3), vc = (lane & 7) ^ ((vr >> 1) & 7);
;         vg[i] = VTp + (size_t)(h * 128 + vr) * NTOK + vc * 8;
;     }
;     const unsigned dmaoff = (unsigned)wid * 2048u;
;     ...
;     int kad[4], vad[4];
; #pragma unroll
;     for (int d0 = 0; d0 < 4; ++d0) kad[d0] = r32 * 256 + (((map * 8 + 2 * d0 + hi) ^ (r32 & 15)) << 4);
; #pragma unroll
;     for (int j = 0; j < 4; ++j) vad[j] = AT_KBYTES + r32 * 128 + (((2 * j + hi) ^ ((r32 >> 1) & 7)) << 4);
;     ...
;     f32x16 o[4];
; #pragma unroll
;     for (int b = 0; b < 4; ++b)
; #pragma unroll
;         for (int r = 0; r < 16; ++r) o[b][r] = 0.f;
;     f32x16 negm;
; #pragma unroll
;     for (int r = 0; r < 16; ++r) negm[r] = negM;
;     float l0 = 0.f, l1 = 0.f;
;     AT_DMA(0); AT_ADV();
;     asm volatile("s_waitcnt vmcnt(0)" ::: "memory");
;     __builtin_amdgcn_s_barrier();
;     AT_DMA(AT_BUF); AT_ADV();
;     f32x16 pa, pb;
;     {
;         f32x16 s0 = negm, s1 = negm;
; #pragma unroll
;         for (int d0 = 0; d0 < 4; ++d0) { s0 = __builtin_amdgcn_mfma_f32_32x32x16_bf16(KFR(0, d0, 0), qf[d0], s0, 0, 0, 0); s1 = __builtin_amdgcn_mfma_f32_32x32x16_bf16(KFR(0, d0, 1), qf[d0], s1, 0, 0, 0); }
; #pragma unroll
;         for (int r = 0; r < 16; ++r) { pa[r] = __builtin_amdgcn_exp2f(s0[r]); pb[r] = __builtin_amdgcn_exp2f(s1[r]); }
;     }
.LBB0_830:
	v_readfirstlane_b32 s25, v220
	s_bfe_u32 s29, s25, 0x20006
	s_lshl_b32 s8, s20, 4
	s_and_b32 s8, s8, 0xffffff80
	s_lshl_b32 s21, s29, 5
	s_or_b32 s21, s21, s8
	s_lshr_b32 s28, s25, 8
	v_or_b32_e32 v16, s21, v153
	s_lshl_b32 s8, s20, 7
	v_ashrrev_i32_e32 v17, 31, v16
	s_and_b32 s24, s8, 0x380
	s_lshl_b32 s8, s28, 6
	v_lshlrev_b64 v[16:17], 11, v[16:17]
	s_add_i32 s8, s8, s24
	v_lshl_add_u64 v[16:17], s[4:5], 0, v[16:17]
	s_lshl_b32 s8, s8, 1
	v_lshl_add_u64 v[16:17], v[16:17], 0, s[8:9]
	v_lshlrev_b32_e32 v130, 4, v150
	s_mov_b64 s[34:35], 0x8000
	v_lshl_add_u64 v[16:17], v[16:17], 0, v[130:131]
	v_lshl_add_u64 v[18:19], v[16:17], 0, s[34:35]
	global_load_dwordx4 v[112:115], v[16:17], off
	global_load_dwordx4 v[116:119], v[16:17], off offset:64
	global_load_dwordx4 v[120:123], v[18:19], off
	global_load_dwordx4 v[124:127], v[18:19], off offset:64
	s_lshr_b32 s33, s25, 6
	s_lshr_b32 s8, s25, 5
	s_lshl_b32 s30, s24, 1
	s_add_u32 s30, s3, s30
	s_addc_u32 s31, s18, 0
	s_lshl_b32 s34, s33, 3
	s_bfe_u32 s98, s25, 0x10007
	s_lshl_b32 s98, s98, 3
	s_or_b32 s99, s98, 4
	v_or_b32_e32 v130, s34, v150
	v_bitop3_b32 v18, s98, v220, v150 bitop3:0x36
	v_lshlrev_b64 v[16:17], 11, v[130:131]
	v_lshlrev_b32_e32 v18, 4, v18
	v_lshl_add_u64 v[16:17], s[30:31], 0, v[16:17]
	v_and_b32_e32 v130, 0xf0, v18
	v_lshl_add_u64 v[56:57], v[16:17], 0, v[130:131]
	v_lshl_or_b32 v16, s33, 4, v151
	v_lshrrev_b32_e32 v17, 1, v151
	v_xor_b32_e32 v20, v17, v220
	v_add_u32_e32 v18, s24, v16
	v_mov_b64_e32 v[16:17], s[6:7]
	v_mad_u64_u32 v[18:19], s[34:35], v18, s19, v[16:17]
	v_lshlrev_b32_e32 v20, 4, v20
	s_or_b32 s8, s8, 1
	v_and_b32_e32 v130, 0x70, v20
	s_lshl_b32 s34, s8, 2
	v_lshl_add_u64 v[58:59], v[18:19], 0, v[130:131]
	v_or_b32_e32 v130, s34, v150
	v_bitop3_b32 v20, s99, v220, v150 bitop3:0x36
	v_lshlrev_b64 v[18:19], 11, v[130:131]
	v_lshlrev_b32_e32 v20, 4, v20
	v_lshl_add_u64 v[18:19], s[30:31], 0, v[18:19]
	v_and_b32_e32 v130, 0xf0, v20
	v_lshl_add_u64 v[60:61], v[18:19], 0, v[130:131]
	v_lshl_or_b32 v18, s8, 3, v151
	v_lshrrev_b32_e32 v19, 1, v18
	v_add_u32_e32 v18, s24, v18
	s_lshl_b32 s8, s33, 11
	v_mad_u64_u32 v[16:17], s[30:31], v18, s19, v[16:17]
	s_add_i32 s8, s8, 0
	v_xor_b32_e32 v19, v19, v220
	s_add_i32 s31, s8, 0x4000
	s_mov_b32 m0, s8
	v_lshlrev_b32_e32 v18, 4, v19
	global_load_lds_dwordx4 v[56:57], off
	s_mov_b32 m0, s31
	v_and_b32_e32 v130, 0x70, v18
	global_load_lds_dwordx4 v[58:59], off
	s_add_i32 m0, s8, 0x400
	v_lshl_add_u64 v[62:63], v[16:17], 0, v[130:131]
	global_load_lds_dwordx4 v[60:61], off
	s_add_i32 m0, s8, 0x4400
	v_lshl_add_u64 v[16:17], v[56:57], 0, s[10:11]
	global_load_lds_dwordx4 v[62:63], off
	s_add_i32 m0, s8, 0x8000
	s_add_i32 s31, s8, 0xc000
	v_lshl_add_u64 v[20:21], v[58:59], 0, s[12:13]
	s_waitcnt vmcnt(0)
	s_barrier
	global_load_lds_dwordx4 v[16:17], off
	s_mov_b32 m0, s31
	v_lshl_add_u64 v[18:19], v[60:61], 0, s[10:11]
	global_load_lds_dwordx4 v[20:21], off
	s_add_i32 m0, s8, 0x8400
	v_lshl_add_u64 v[22:23], v[62:63], 0, s[12:13]
	global_load_lds_dwordx4 v[18:19], off
	s_add_i32 m0, s8, 0xc400
	s_lshl_b32 s30, s28, 3
	global_load_lds_dwordx4 v[22:23], off
	v_lshl_add_u64 v[140:141], v[56:57], 0, s[14:15]
	v_lshl_add_u64 v[142:143], v[60:61], 0, s[14:15]
	v_lshl_add_u64 v[144:145], v[58:59], 0, s[16:17]
	v_lshl_add_u64 v[146:147], v[62:63], 0, s[16:17]
	s_add_i32 m0, s8, 0x10000
	s_nop 0
	global_load_lds_dwordx4 v[140:141], off
	s_add_i32 m0, s8, 0x14000
	s_nop 0
	global_load_lds_dwordx4 v[144:145], off
	s_add_i32 m0, s8, 0x10400
	s_nop 0
	global_load_lds_dwordx4 v[142:143], off
	s_add_i32 m0, s8, 0x14400
	s_nop 0
	global_load_lds_dwordx4 v[146:147], off
	v_lshl_add_u64 v[140:141], v[140:141], 0, s[10:11]
	v_lshl_add_u64 v[142:143], v[142:143], 0, s[10:11]
	v_lshl_add_u64 v[144:145], v[144:145], 0, s[12:13]
	v_lshl_add_u64 v[146:147], v[146:147], 0, s[12:13]
	s_mov_b32 s98, s3
	s_mov_b32 s99, s18
	s_mov_b64 s[100:101], s[6:7]
	v_subrev_u32_e32 v140, s3, v140
	v_subrev_u32_e32 v142, s3, v142
	v_subrev_u32_e32 v144, s6, v144
	v_subrev_u32_e32 v146, s6, v146
	s_mov_b32 s33, 1
	v_bitop3_b32 v24, s30, v153, v150 bitop3:0x36
	v_lshlrev_b32_e32 v25, 8, v153
	v_and_b32_e32 v26, 0x700, v25
	v_and_b32_e32 v25, 0x800, v25
	v_lshl_or_b32 v26, v25, 1, v26
	v_lshl_add_u32 v198, v24, 4, v26
	v_xor_b32_e32 v200, 64, v198
	v_lshrrev_b32_e32 v24, 1, v153
	v_xor_b32_e32 v24, v24, v150
	v_lshlrev_b32_e32 v25, 7, v153
	v_lshl_add_u32 v201, v24, 4, v25
	v_xor_b32_e32 v202, 64, v201
	v_add_u32_e32 v247, 0x10000, v198
	v_add_u32_e32 v248, 0x10000, v200
	v_add_u32_e32 v249, 0x10000, v201
	v_add_u32_e32 v250, 0x10000, v202
	ds_read_b128 v[16:19], v198
	ds_read_b128 v[20:23], v200
	ds_read_b128 v[24:27], v198 offset:2048
	ds_read_b128 v[28:31], v200 offset:2048
	ds_read_b128 v[32:35], v198 offset:8192
	ds_read_b128 v[36:39], v200 offset:8192
	ds_read_b128 v[40:43], v198 offset:10240
	ds_read_b128 v[44:47], v200 offset:10240
	s_waitcnt lgkmcnt(7)
	v_mfma_f32_16x16x32_bf16 v[80:83], v[16:19], v[112:115], v[0:3]
	v_mfma_f32_16x16x32_bf16 v[84:87], v[16:19], v[120:123], v[0:3]
	s_waitcnt lgkmcnt(6)
	v_mfma_f32_16x16x32_bf16 v[80:83], v[20:23], v[116:119], v[80:83]
	v_mfma_f32_16x16x32_bf16 v[84:87], v[20:23], v[124:127], v[84:87]
	s_waitcnt lgkmcnt(5)
	v_mfma_f32_16x16x32_bf16 v[88:91], v[24:27], v[112:115], v[0:3]
	v_mfma_f32_16x16x32_bf16 v[92:95], v[24:27], v[120:123], v[0:3]
	s_waitcnt lgkmcnt(4)
	v_mfma_f32_16x16x32_bf16 v[88:91], v[28:31], v[116:119], v[88:91]
	v_mfma_f32_16x16x32_bf16 v[92:95], v[28:31], v[124:127], v[92:95]
	s_waitcnt lgkmcnt(3)
	v_mfma_f32_16x16x32_bf16 v[96:99], v[32:35], v[112:115], v[0:3]
	v_mfma_f32_16x16x32_bf16 v[100:103], v[32:35], v[120:123], v[0:3]
	s_waitcnt lgkmcnt(2)
; __device__ __forceinline__ unsigned cvtpk(float lo, float hi) { f32x2 v = {lo, hi}; bf16x2_t b = __builtin_convertvector(v, bf16x2_t); return __builtin_bit_cast(unsigned, b); }
; #define SB() __builtin_amdgcn_sched_barrier(0)
; __device__ __forceinline__ void attn_unit(unsigned char* ws, const float* sub_g, LAS unsigned char* lds, int h, int qb, float negM, float lam) {
;     ...
;     {
;         f32x16 s0 = negm, s1 = negm;
; #pragma unroll
;         for (int d0 = 0; d0 < 4; ++d0) { s0 = __builtin_amdgcn_mfma_f32_32x32x16_bf16(KFR(0, d0, 0), qf[d0], s0, 0, 0, 0); s1 = __builtin_amdgcn_mfma_f32_32x32x16_bf16(KFR(0, d0, 1), qf[d0], s1, 0, 0, 0); }
; #pragma unroll
;         for (int r = 0; r < 16; ++r) { pa[r] = __builtin_amdgcn_exp2f(s0[r]); pb[r] = __builtin_amdgcn_exp2f(s1[r]); }
;     }
;     asm volatile("s_waitcnt vmcnt(0) lgkmcnt(0)" ::: "memory");
;     __builtin_amdgcn_s_barrier();
;     int bV = 0, bK = AT_BUF, bW = 2 * AT_BUF;
;     u32x4 pw[4];
;     for (int t = 1; t < AT_NT; ++t) {
;         AT_DMA(bW);
;         if (t + 2 < AT_NT) AT_ADV();
;         SB();
;     ...
;         f32x16 s0, s1;
;         bf16x8 F0 = FLOAD(0), F1 = FLOAD(1), F2;
;         SB();
;         F2 = FLOAD(2); s0 = __builtin_amdgcn_mfma_f32_32x32x16_bf16(F0, qf[0], negm, 0, 0, 0); ADD4(pa, 0); pw[0][0] = cvtpk(pa[0], pa[1]); SB();
;         F0 = FLOAD(3); s1 = __builtin_amdgcn_mfma_f32_32x32x16_bf16(F1, qf[0], negm, 0, 0, 0); ADD4(pa, 4); pw[0][1] = cvtpk(pa[2], pa[3]); SB();
;         F1 = FLOAD(4); s0 = __builtin_amdgcn_mfma_f32_32x32x16_bf16(F2, qf[1], s0, 0, 0, 0); ADD4(pa, 8); pw[0][2] = cvtpk(pa[4], pa[5]); SB();
;         F2 = FLOAD(5); s1 = __builtin_amdgcn_mfma_f32_32x32x16_bf16(F0, qf[1], s1, 0, 0, 0); ADD4(pa, 12); pw[0][3] = cvtpk(pa[6], pa[7]); SB();
;         F0 = FLOAD(6); s0 = __builtin_amdgcn_mfma_f32_32x32x16_bf16(F1, qf[2], s0, 0, 0, 0); ADD4(pb, 0); pw[1][0] = cvtpk(pa[8], pa[9]); SB();
;         F1 = FLOAD(7); s1 = __builtin_amdgcn_mfma_f32_32x32x16_bf16(F2, qf[2], s1, 0, 0, 0); ADD4(pb, 4); pw[1][1] = cvtpk(pa[10], pa[11]); SB();
;         F2 = FLOAD(8); s0 = __builtin_amdgcn_mfma_f32_32x32x16_bf16(F0, qf[3], s0, 0, 0, 0); ADD4(pb, 8); pw[1][2] = cvtpk(pa[12], pa[13]); SB();
;         F0 = FLOAD(9); s1 = __builtin_amdgcn_mfma_f32_32x32x16_bf16(F1, qf[3], s1, 0, 0, 0); ADD4(pb, 12); pw[1][3] = cvtpk(pa[14], pa[15]); SB();
	v_mfma_f32_16x16x32_bf16 v[96:99], v[36:39], v[116:119], v[96:99]
	v_mfma_f32_16x16x32_bf16 v[100:103], v[36:39], v[124:127], v[100:103]
	s_waitcnt lgkmcnt(1)
	v_mfma_f32_16x16x32_bf16 v[104:107], v[40:43], v[112:115], v[0:3]
	v_mfma_f32_16x16x32_bf16 v[108:111], v[40:43], v[120:123], v[0:3]
	s_waitcnt lgkmcnt(0)
	v_mfma_f32_16x16x32_bf16 v[104:107], v[44:47], v[116:119], v[104:107]
	v_mfma_f32_16x16x32_bf16 v[108:111], v[44:47], v[124:127], v[108:111]
	s_nop 7
	s_nop 1
	v_exp_f32_e32 v183, v80
	v_exp_f32_e32 v184, v81
	v_exp_f32_e32 v185, v82
	v_exp_f32_e32 v186, v83
	v_exp_f32_e32 v187, v84
	v_exp_f32_e32 v188, v85
	v_exp_f32_e32 v189, v86
	v_exp_f32_e32 v190, v87
	v_exp_f32_e32 v191, v88
	v_exp_f32_e32 v192, v89
	v_exp_f32_e32 v193, v90
	v_exp_f32_e32 v194, v91
	v_exp_f32_e32 v195, v92
	v_exp_f32_e32 v196, v93
	v_exp_f32_e32 v197, v94
	v_exp_f32_e32 v199, v95
	v_exp_f32_e32 v203, v96
	v_exp_f32_e32 v204, v97
	v_exp_f32_e32 v205, v98
	v_exp_f32_e32 v206, v99
	v_exp_f32_e32 v207, v100
	v_exp_f32_e32 v208, v101
	v_exp_f32_e32 v209, v102
	v_exp_f32_e32 v210, v103
	v_exp_f32_e32 v211, v104
	v_exp_f32_e32 v213, v105
	v_exp_f32_e32 v214, v106
	v_exp_f32_e32 v215, v107
	v_exp_f32_e32 v216, v108
	v_exp_f32_e32 v217, v109
	v_exp_f32_e32 v218, v110
	v_exp_f32_e32 v219, v111
	v_mov_b32_e32 v16, 0
	v_mov_b32_e32 v17, 0
	v_mov_b32_e32 v18, 0
	v_mov_b32_e32 v19, 0
	v_mov_b32_e32 v20, 0
	v_mov_b32_e32 v21, 0
	v_mov_b32_e32 v22, 0
	v_mov_b32_e32 v23, 0
	v_mov_b32_e32 v24, 0
	v_mov_b32_e32 v25, 0
	v_mov_b32_e32 v26, 0
	v_mov_b32_e32 v27, 0
	v_mov_b32_e32 v28, 0
	v_mov_b32_e32 v29, 0
	v_mov_b32_e32 v30, 0
	v_mov_b32_e32 v31, 0
	v_mov_b32_e32 v32, 0
	v_mov_b32_e32 v33, 0
	v_mov_b32_e32 v34, 0
	v_mov_b32_e32 v35, 0
	v_mov_b32_e32 v36, 0
	v_mov_b32_e32 v37, 0
	v_mov_b32_e32 v38, 0
	v_mov_b32_e32 v39, 0
	v_mov_b32_e32 v40, 0
	v_mov_b32_e32 v41, 0
	v_mov_b32_e32 v42, 0
	v_mov_b32_e32 v43, 0
	v_mov_b32_e32 v44, 0
	v_mov_b32_e32 v45, 0
	v_mov_b32_e32 v46, 0
	v_mov_b32_e32 v47, 0
	v_mov_b32_e32 v48, 0
	v_mov_b32_e32 v49, 0
	v_mov_b32_e32 v50, 0
	v_mov_b32_e32 v51, 0
	v_mov_b32_e32 v52, 0
	v_mov_b32_e32 v53, 0
	v_mov_b32_e32 v54, 0
	v_mov_b32_e32 v55, 0
	v_mov_b32_e32 v56, 0
	v_mov_b32_e32 v57, 0
	v_mov_b32_e32 v58, 0
	v_mov_b32_e32 v59, 0
	v_mov_b32_e32 v60, 0
	v_mov_b32_e32 v61, 0
	v_mov_b32_e32 v62, 0
	v_mov_b32_e32 v63, 0
	v_mov_b32_e32 v64, 0
	v_mov_b32_e32 v65, 0
	v_mov_b32_e32 v66, 0
	v_mov_b32_e32 v67, 0
	v_mov_b32_e32 v68, 0
	v_mov_b32_e32 v69, 0
	v_mov_b32_e32 v70, 0
	v_mov_b32_e32 v71, 0
	v_mov_b32_e32 v72, 0
	v_mov_b32_e32 v73, 0
	v_mov_b32_e32 v74, 0
	v_mov_b32_e32 v75, 0
	v_mov_b32_e32 v76, 0
	v_mov_b32_e32 v77, 0
	v_mov_b32_e32 v78, 0
	v_mov_b32_e32 v79, 0
	v_mov_b32_e32 v222, 0
	v_mov_b32_e32 v223, 0
	s_waitcnt vmcnt(4)
	s_barrier
	ds_read_b128 v[4:7], v198 offset:32768
	ds_read_b128 v[8:11], v200 offset:32768
	ds_read_b128 v[12:15], v198 offset:34816
	s_branch .Lattn_c1
.Lattn_c1:
	s_waitcnt lgkmcnt(2)
	v_mfma_f32_16x16x32_bf16 v[80:83], v[4:7], v[112:115], v[0:3]
	ds_read_b128 v[224:227], v200 offset:34816
	v_add_f32_e32 v222, v222, v183
	v_add_f32_e32 v223, v223, v187
	v_cvt_pk_bf16_f32 v232, v183, v184
	v_mfma_f32_16x16x32_bf16 v[84:87], v[4:7], v[120:123], v[0:3]
	v_add_f32_e32 v222, v222, v184
	v_add_f32_e32 v223, v223, v188
	s_waitcnt lgkmcnt(2)
	v_mfma_f32_16x16x32_bf16 v[80:83], v[8:11], v[116:119], v[80:83]
	ds_read_b128 v[4:7], v198 offset:40960
	v_add_f32_e32 v222, v222, v185
	v_add_f32_e32 v223, v223, v189
	v_cvt_pk_bf16_f32 v233, v185, v186
	v_mfma_f32_16x16x32_bf16 v[84:87], v[8:11], v[124:127], v[84:87]
	v_add_f32_e32 v222, v222, v186
	v_add_f32_e32 v223, v223, v190
	s_waitcnt lgkmcnt(2)
	v_mfma_f32_16x16x32_bf16 v[88:91], v[12:15], v[112:115], v[0:3]
	ds_read_b128 v[8:11], v200 offset:40960
	v_add_f32_e32 v222, v222, v191
	v_add_f32_e32 v223, v223, v195
	v_cvt_pk_bf16_f32 v234, v191, v192
	v_mfma_f32_16x16x32_bf16 v[92:95], v[12:15], v[120:123], v[0:3]
	v_add_f32_e32 v222, v222, v192
	v_add_f32_e32 v223, v223, v196
	s_waitcnt lgkmcnt(2)
	v_mfma_f32_16x16x32_bf16 v[88:91], v[224:227], v[116:119], v[88:91]
	ds_read_b128 v[12:15], v198 offset:43008
	v_add_f32_e32 v222, v222, v193
	v_add_f32_e32 v223, v223, v197
	v_cvt_pk_bf16_f32 v235, v193, v194
	v_mfma_f32_16x16x32_bf16 v[92:95], v[224:227], v[124:127], v[92:95]
	v_add_f32_e32 v222, v222, v194
	v_add_f32_e32 v223, v223, v199
	s_waitcnt lgkmcnt(2)
	v_mfma_f32_16x16x32_bf16 v[96:99], v[4:7], v[112:115], v[0:3]
	ds_read_b128 v[224:227], v200 offset:43008
	v_add_f32_e32 v222, v222, v203
	v_add_f32_e32 v223, v223, v207
	v_cvt_pk_bf16_f32 v236, v187, v188
	v_mfma_f32_16x16x32_bf16 v[100:103], v[4:7], v[120:123], v[0:3]
	v_add_f32_e32 v222, v222, v204
	v_add_f32_e32 v223, v223, v208
	s_waitcnt lgkmcnt(2)
	v_mfma_f32_16x16x32_bf16 v[96:99], v[8:11], v[116:119], v[96:99]
	ds_read_b128 v[4:7], v201 offset:16384
	v_add_f32_e32 v222, v222, v205
	v_add_f32_e32 v223, v223, v209
	v_cvt_pk_bf16_f32 v237, v189, v190
	v_mfma_f32_16x16x32_bf16 v[100:103], v[8:11], v[124:127], v[100:103]
	v_add_f32_e32 v222, v222, v206
	v_add_f32_e32 v223, v223, v210
	s_waitcnt lgkmcnt(2)
	v_mfma_f32_16x16x32_bf16 v[104:107], v[12:15], v[112:115], v[0:3]
	ds_read_b128 v[8:11], v201 offset:18432
	v_add_f32_e32 v222, v222, v211
	v_add_f32_e32 v223, v223, v216
	v_cvt_pk_bf16_f32 v238, v195, v196
	v_mfma_f32_16x16x32_bf16 v[108:111], v[12:15], v[120:123], v[0:3]
	v_add_f32_e32 v222, v222, v213
	v_add_f32_e32 v223, v223, v217
	s_waitcnt lgkmcnt(2)
	v_mfma_f32_16x16x32_bf16 v[104:107], v[224:227], v[116:119], v[104:107]
	ds_read_b128 v[12:15], v201 offset:20480
	v_add_f32_e32 v222, v222, v214
	v_add_f32_e32 v223, v223, v218
	v_cvt_pk_bf16_f32 v239, v197, v199
	v_mfma_f32_16x16x32_bf16 v[108:111], v[224:227], v[124:127], v[108:111]
	v_add_f32_e32 v222, v222, v215
	v_add_f32_e32 v223, v223, v219
	s_waitcnt vmcnt(0)
	s_barrier
; __device__ __forceinline__ void attn_unit(unsigned char* ws, const float* sub_g, LAS unsigned char* lds, int h, int qb, float negM, float lam) {
;     ...
;         F1 = FLOAD(10); o[0] = __builtin_amdgcn_mfma_f32_32x32x16_bf16(F2, __builtin_bit_cast(bf16x8, pw[0]), o[0], 0, 0, 0); pw[2][0] = cvtpk(pb[0], pb[1]); EXP2(s0, pa, 0); SB();
;         F2 = FLOAD(11); o[1] = __builtin_amdgcn_mfma_f32_32x32x16_bf16(F0, __builtin_bit_cast(bf16x8, pw[0]), o[1], 0, 0, 0); pw[2][1] = cvtpk(pb[2], pb[3]); EXP2(s0, pa, 2); SB();
;         F0 = FLOAD(12); o[2] = __builtin_amdgcn_mfma_f32_32x32x16_bf16(F1, __builtin_bit_cast(bf16x8, pw[0]), o[2], 0, 0, 0); pw[2][2] = cvtpk(pb[4], pb[5]); EXP2(s0, pa, 4); SB();
;         F1 = FLOAD(13); o[3] = __builtin_amdgcn_mfma_f32_32x32x16_bf16(F2, __builtin_bit_cast(bf16x8, pw[0]), o[3], 0, 0, 0); pw[2][3] = cvtpk(pb[6], pb[7]); EXP2(s0, pa, 6); SB();
;         F2 = FLOAD(14); o[0] = __builtin_amdgcn_mfma_f32_32x32x16_bf16(F0, __builtin_bit_cast(bf16x8, pw[1]), o[0], 0, 0, 0); pw[3][0] = cvtpk(pb[8], pb[9]); EXP2(s0, pa, 8); SB();
;         F0 = FLOAD(15); o[1] = __builtin_amdgcn_mfma_f32_32x32x16_bf16(F1, __builtin_bit_cast(bf16x8, pw[1]), o[1], 0, 0, 0); pw[3][1] = cvtpk(pb[10], pb[11]); EXP2(s0, pa, 10); SB();
;         F1 = FLOAD(16); o[2] = __builtin_amdgcn_mfma_f32_32x32x16_bf16(F2, __builtin_bit_cast(bf16x8, pw[1]), o[2], 0, 0, 0); pw[3][2] = cvtpk(pb[12], pb[13]); EXP2(s0, pa, 12); SB();
;         F2 = FLOAD(17); o[3] = __builtin_amdgcn_mfma_f32_32x32x16_bf16(F0, __builtin_bit_cast(bf16x8, pw[1]), o[3], 0, 0, 0); pw[3][3] = cvtpk(pb[14], pb[15]); EXP2(s0, pa, 14); SB();
;         F0 = FLOAD(18); o[0] = __builtin_amdgcn_mfma_f32_32x32x16_bf16(F1, __builtin_bit_cast(bf16x8, pw[2]), o[0], 0, 0, 0); EXP2(s1, pb, 0); SB();
;         F1 = FLOAD(19); o[1] = __builtin_amdgcn_mfma_f32_32x32x16_bf16(F2, __builtin_bit_cast(bf16x8, pw[2]), o[1], 0, 0, 0); EXP2(s1, pb, 2); SB();
;         F2 = FLOAD(20); o[2] = __builtin_amdgcn_mfma_f32_32x32x16_bf16(F0, __builtin_bit_cast(bf16x8, pw[2]), o[2], 0, 0, 0); EXP2(s1, pb, 4); SB();
;         F0 = FLOAD(21); o[3] = __builtin_amdgcn_mfma_f32_32x32x16_bf16(F1, __builtin_bit_cast(bf16x8, pw[2]), o[3], 0, 0, 0); EXP2(s1, pb, 6); SB();
;         F1 = FLOAD(22); o[0] = __builtin_amdgcn_mfma_f32_32x32x16_bf16(F2, __builtin_bit_cast(bf16x8, pw[3]), o[0], 0, 0, 0); EXP2(s1, pb, 8); SB();
	s_waitcnt lgkmcnt(2)
	v_mfma_f32_16x16x32_bf16 v[64:67], v[4:7], v[232:235], v[64:67]
	s_add_i32 m0, s8, 0x18000
	ds_read_b128 v[224:227], v201 offset:22528
	global_load_lds_dwordx4 v140, s[98:99]
	v_exp_f32_e32 v183, v80
	v_cvt_pk_bf16_f32 v228, v203, v204
	v_mfma_f32_16x16x32_bf16 v[68:71], v[4:7], v[236:239], v[68:71]
	v_exp_f32_e32 v184, v81
	s_waitcnt lgkmcnt(2)
	v_mfma_f32_16x16x32_bf16 v[72:75], v[8:11], v[232:235], v[72:75]
	s_add_i32 m0, m0, 0x4000
	ds_read_b128 v[4:7], v201 offset:24576
	global_load_lds_dwordx4 v144, s[100:101]
	v_exp_f32_e32 v185, v82
	v_cvt_pk_bf16_f32 v229, v205, v206
	v_mfma_f32_16x16x32_bf16 v[76:79], v[8:11], v[236:239], v[76:79]
	v_exp_f32_e32 v186, v83
	s_waitcnt lgkmcnt(2)
	v_mfma_f32_16x16x32_bf16 v[48:51], v[12:15], v[232:235], v[48:51]
	s_add_i32 m0, m0, 0xffffc400
	ds_read_b128 v[8:11], v201 offset:26624
	global_load_lds_dwordx4 v142, s[98:99]
	v_exp_f32_e32 v187, v84
	v_cvt_pk_bf16_f32 v230, v211, v213
	v_mfma_f32_16x16x32_bf16 v[52:55], v[12:15], v[236:239], v[52:55]
	v_exp_f32_e32 v188, v85
	s_waitcnt lgkmcnt(2)
	v_mfma_f32_16x16x32_bf16 v[56:59], v[224:227], v[232:235], v[56:59]
	s_add_i32 m0, m0, 0x4000
	ds_read_b128 v[12:15], v201 offset:28672
	global_load_lds_dwordx4 v146, s[100:101]
	s_add_u32 s98, s98, 0x20000
	s_addc_u32 s99, s99, 0
	s_add_u32 s100, s100, 0x80
	s_addc_u32 s101, s101, 0
	v_exp_f32_e32 v189, v86
	v_cvt_pk_bf16_f32 v231, v214, v215
	v_mfma_f32_16x16x32_bf16 v[60:63], v[224:227], v[236:239], v[60:63]
	v_exp_f32_e32 v190, v87
	s_waitcnt lgkmcnt(2)
	v_mfma_f32_16x16x32_bf16 v[32:35], v[4:7], v[232:235], v[32:35]
	ds_read_b128 v[224:227], v201 offset:30720
	v_exp_f32_e32 v191, v88
	v_cvt_pk_bf16_f32 v240, v207, v208
	v_mfma_f32_16x16x32_bf16 v[36:39], v[4:7], v[236:239], v[36:39]
	v_exp_f32_e32 v192, v89
	s_waitcnt lgkmcnt(2)
	v_mfma_f32_16x16x32_bf16 v[40:43], v[8:11], v[232:235], v[40:43]
	ds_read_b128 v[4:7], v202 offset:16384
	v_exp_f32_e32 v193, v90
	v_cvt_pk_bf16_f32 v241, v209, v210
	v_mfma_f32_16x16x32_bf16 v[44:47], v[8:11], v[236:239], v[44:47]
	v_exp_f32_e32 v194, v91
	s_waitcnt lgkmcnt(2)
	v_mfma_f32_16x16x32_bf16 v[16:19], v[12:15], v[232:235], v[16:19]
	ds_read_b128 v[8:11], v202 offset:18432
	v_exp_f32_e32 v195, v92
	v_cvt_pk_bf16_f32 v242, v216, v217
	v_mfma_f32_16x16x32_bf16 v[20:23], v[12:15], v[236:239], v[20:23]
	v_exp_f32_e32 v196, v93
	s_waitcnt lgkmcnt(2)
	v_mfma_f32_16x16x32_bf16 v[24:27], v[224:227], v[232:235], v[24:27]
	ds_read_b128 v[12:15], v202 offset:20480
	v_exp_f32_e32 v197, v94
	v_cvt_pk_bf16_f32 v243, v218, v219
	v_mfma_f32_16x16x32_bf16 v[28:31], v[224:227], v[236:239], v[28:31]
	v_exp_f32_e32 v199, v95
	s_waitcnt lgkmcnt(2)
	v_mfma_f32_16x16x32_bf16 v[64:67], v[4:7], v[228:231], v[64:67]
	ds_read_b128 v[224:227], v202 offset:22528
	v_exp_f32_e32 v203, v96
	v_mfma_f32_16x16x32_bf16 v[68:71], v[4:7], v[240:243], v[68:71]
	v_exp_f32_e32 v204, v97
	s_waitcnt lgkmcnt(2)
	v_mfma_f32_16x16x32_bf16 v[72:75], v[8:11], v[228:231], v[72:75]
	ds_read_b128 v[4:7], v202 offset:24576
	v_exp_f32_e32 v205, v98
	v_mfma_f32_16x16x32_bf16 v[76:79], v[8:11], v[240:243], v[76:79]
	v_exp_f32_e32 v206, v99
	s_waitcnt lgkmcnt(2)
	v_mfma_f32_16x16x32_bf16 v[48:51], v[12:15], v[228:231], v[48:51]
	ds_read_b128 v[8:11], v202 offset:26624
	v_exp_f32_e32 v207, v100
	v_mfma_f32_16x16x32_bf16 v[52:55], v[12:15], v[240:243], v[52:55]
	v_exp_f32_e32 v208, v101
	s_waitcnt lgkmcnt(2)
	v_mfma_f32_16x16x32_bf16 v[56:59], v[224:227], v[228:231], v[56:59]
	ds_read_b128 v[12:15], v202 offset:28672
	v_exp_f32_e32 v209, v102
	v_mfma_f32_16x16x32_bf16 v[60:63], v[224:227], v[240:243], v[60:63]
	v_exp_f32_e32 v210, v103
	s_waitcnt lgkmcnt(2)
	v_mfma_f32_16x16x32_bf16 v[32:35], v[4:7], v[228:231], v[32:35]
	ds_read_b128 v[224:227], v202 offset:30720
	v_exp_f32_e32 v211, v104
	v_mfma_f32_16x16x32_bf16 v[36:39], v[4:7], v[240:243], v[36:39]
	v_exp_f32_e32 v213, v105
	s_waitcnt lgkmcnt(2)
	v_mfma_f32_16x16x32_bf16 v[40:43], v[8:11], v[228:231], v[40:43]
	ds_read_b128 v[4:7], v247
	v_exp_f32_e32 v214, v106
	v_mfma_f32_16x16x32_bf16 v[44:47], v[8:11], v[240:243], v[44:47]
	v_exp_f32_e32 v215, v107
	s_waitcnt lgkmcnt(2)
	v_mfma_f32_16x16x32_bf16 v[16:19], v[12:15], v[228:231], v[16:19]
	ds_read_b128 v[8:11], v248
	v_exp_f32_e32 v216, v108
	v_mfma_f32_16x16x32_bf16 v[20:23], v[12:15], v[240:243], v[20:23]
	v_exp_f32_e32 v217, v109
	s_waitcnt lgkmcnt(2)
	v_mfma_f32_16x16x32_bf16 v[24:27], v[224:227], v[228:231], v[24:27]
	ds_read_b128 v[12:15], v247 offset:2048
	v_exp_f32_e32 v218, v110
	v_mfma_f32_16x16x32_bf16 v[28:31], v[224:227], v[240:243], v[28:31]
	v_exp_f32_e32 v219, v111
	s_add_i32 s33, s33, 1
; #define SB() __builtin_amdgcn_sched_barrier(0)
; __device__ __forceinline__ void attn_unit(unsigned char* ws, const float* sub_g, LAS unsigned char* lds, int h, int qb, float negM, float lam) {
;     ...
;         bf16x8 F0 = FLOAD(0), F1 = FLOAD(1), F2;
;         SB();
;         F2 = FLOAD(2); s0 = __builtin_amdgcn_mfma_f32_32x32x16_bf16(F0, qf[0], negm, 0, 0, 0); ADD4(pa, 0); pw[0][0] = cvtpk(pa[0], pa[1]); SB();
;         F0 = FLOAD(3); s1 = __builtin_amdgcn_mfma_f32_32x32x16_bf16(F1, qf[0], negm, 0, 0, 0); ADD4(pa, 4); pw[0][1] = cvtpk(pa[2], pa[3]); SB();
;         F1 = FLOAD(4); s0 = __builtin_amdgcn_mfma_f32_32x32x16_bf16(F2, qf[1], s0, 0, 0, 0); ADD4(pa, 8); pw[0][2] = cvtpk(pa[4], pa[5]); SB();
;         F2 = FLOAD(5); s1 = __builtin_amdgcn_mfma_f32_32x32x16_bf16(F0, qf[1], s1, 0, 0, 0); ADD4(pa, 12); pw[0][3] = cvtpk(pa[6], pa[7]); SB();
;         F0 = FLOAD(6); s0 = __builtin_amdgcn_mfma_f32_32x32x16_bf16(F1, qf[2], s0, 0, 0, 0); ADD4(pb, 0); pw[1][0] = cvtpk(pa[8], pa[9]); SB();
;         F1 = FLOAD(7); s1 = __builtin_amdgcn_mfma_f32_32x32x16_bf16(F2, qf[2], s1, 0, 0, 0); ADD4(pb, 4); pw[1][1] = cvtpk(pa[10], pa[11]); SB();
;         F2 = FLOAD(8); s0 = __builtin_amdgcn_mfma_f32_32x32x16_bf16(F0, qf[3], s0, 0, 0, 0); ADD4(pb, 8); pw[1][2] = cvtpk(pa[12], pa[13]); SB();
;         F0 = FLOAD(9); s1 = __builtin_amdgcn_mfma_f32_32x32x16_bf16(F1, qf[3], s1, 0, 0, 0); ADD4(pb, 12); pw[1][3] = cvtpk(pa[14], pa[15]); SB();
;         F1 = FLOAD(10); o[0] = __builtin_amdgcn_mfma_f32_32x32x16_bf16(F2, __builtin_bit_cast(bf16x8, pw[0]), o[0], 0, 0, 0); pw[2][0] = cvtpk(pb[0], pb[1]); EXP2(s0, pa, 0); SB();
;         F2 = FLOAD(11); o[1] = __builtin_amdgcn_mfma_f32_32x32x16_bf16(F0, __builtin_bit_cast(bf16x8, pw[0]), o[1], 0, 0, 0); pw[2][1] = cvtpk(pb[2], pb[3]); EXP2(s0, pa, 2); SB();
;         F0 = FLOAD(12); o[2] = __builtin_amdgcn_mfma_f32_32x32x16_bf16(F1, __builtin_bit_cast(bf16x8, pw[0]), o[2], 0, 0, 0); pw[2][2] = cvtpk(pb[4], pb[5]); EXP2(s0, pa, 4); SB();
;         F1 = FLOAD(13); o[3] = __builtin_amdgcn_mfma_f32_32x32x16_bf16(F2, __builtin_bit_cast(bf16x8, pw[0]), o[3], 0, 0, 0); pw[2][3] = cvtpk(pb[6], pb[7]); EXP2(s0, pa, 6); SB();
;         F2 = FLOAD(14); o[0] = __builtin_amdgcn_mfma_f32_32x32x16_bf16(F0, __builtin_bit_cast(bf16x8, pw[1]), o[0], 0, 0, 0); pw[3][0] = cvtpk(pb[8], pb[9]); EXP2(s0, pa, 8); SB();
.Lattn_c2:
	s_waitcnt lgkmcnt(2)
	v_mfma_f32_16x16x32_bf16 v[80:83], v[4:7], v[112:115], v[0:3]
	ds_read_b128 v[224:227], v248 offset:2048
	v_add_f32_e32 v222, v222, v183
	v_add_f32_e32 v223, v223, v187
	v_cvt_pk_bf16_f32 v232, v183, v184
	v_mfma_f32_16x16x32_bf16 v[84:87], v[4:7], v[120:123], v[0:3]
	v_add_f32_e32 v222, v222, v184
	v_add_f32_e32 v223, v223, v188
	s_waitcnt lgkmcnt(2)
	v_mfma_f32_16x16x32_bf16 v[80:83], v[8:11], v[116:119], v[80:83]
	ds_read_b128 v[4:7], v247 offset:8192
	v_add_f32_e32 v222, v222, v185
	v_add_f32_e32 v223, v223, v189
	v_cvt_pk_bf16_f32 v233, v185, v186
	v_mfma_f32_16x16x32_bf16 v[84:87], v[8:11], v[124:127], v[84:87]
	v_add_f32_e32 v222, v222, v186
	v_add_f32_e32 v223, v223, v190
	s_waitcnt lgkmcnt(2)
	v_mfma_f32_16x16x32_bf16 v[88:91], v[12:15], v[112:115], v[0:3]
	ds_read_b128 v[8:11], v248 offset:8192
	v_add_f32_e32 v222, v222, v191
	v_add_f32_e32 v223, v223, v195
	v_cvt_pk_bf16_f32 v234, v191, v192
	v_mfma_f32_16x16x32_bf16 v[92:95], v[12:15], v[120:123], v[0:3]
	v_add_f32_e32 v222, v222, v192
	v_add_f32_e32 v223, v223, v196
	s_waitcnt lgkmcnt(2)
	v_mfma_f32_16x16x32_bf16 v[88:91], v[224:227], v[116:119], v[88:91]
	ds_read_b128 v[12:15], v247 offset:10240
	v_add_f32_e32 v222, v222, v193
	v_add_f32_e32 v223, v223, v197
	v_cvt_pk_bf16_f32 v235, v193, v194
	v_mfma_f32_16x16x32_bf16 v[92:95], v[224:227], v[124:127], v[92:95]
	v_add_f32_e32 v222, v222, v194
	v_add_f32_e32 v223, v223, v199
	s_waitcnt lgkmcnt(2)
	v_mfma_f32_16x16x32_bf16 v[96:99], v[4:7], v[112:115], v[0:3]
	ds_read_b128 v[224:227], v248 offset:10240
	v_add_f32_e32 v222, v222, v203
	v_add_f32_e32 v223, v223, v207
	v_cvt_pk_bf16_f32 v236, v187, v188
	v_mfma_f32_16x16x32_bf16 v[100:103], v[4:7], v[120:123], v[0:3]
	v_add_f32_e32 v222, v222, v204
	v_add_f32_e32 v223, v223, v208
	s_waitcnt lgkmcnt(2)
	v_mfma_f32_16x16x32_bf16 v[96:99], v[8:11], v[116:119], v[96:99]
	ds_read_b128 v[4:7], v201 offset:49152
	v_add_f32_e32 v222, v222, v205
	v_add_f32_e32 v223, v223, v209
	v_cvt_pk_bf16_f32 v237, v189, v190
	v_mfma_f32_16x16x32_bf16 v[100:103], v[8:11], v[124:127], v[100:103]
	v_add_f32_e32 v222, v222, v206
	v_add_f32_e32 v223, v223, v210
	s_waitcnt lgkmcnt(2)
	v_mfma_f32_16x16x32_bf16 v[104:107], v[12:15], v[112:115], v[0:3]
	ds_read_b128 v[8:11], v201 offset:51200
	v_add_f32_e32 v222, v222, v211
	v_add_f32_e32 v223, v223, v216
	v_cvt_pk_bf16_f32 v238, v195, v196
	v_mfma_f32_16x16x32_bf16 v[108:111], v[12:15], v[120:123], v[0:3]
	v_add_f32_e32 v222, v222, v213
	v_add_f32_e32 v223, v223, v217
	s_waitcnt lgkmcnt(2)
	v_mfma_f32_16x16x32_bf16 v[104:107], v[224:227], v[116:119], v[104:107]
	ds_read_b128 v[12:15], v201 offset:53248
	v_add_f32_e32 v222, v222, v214
	v_add_f32_e32 v223, v223, v218
	v_cvt_pk_bf16_f32 v239, v197, v199
	v_mfma_f32_16x16x32_bf16 v[108:111], v[224:227], v[124:127], v[108:111]
	v_add_f32_e32 v222, v222, v215
	v_add_f32_e32 v223, v223, v219
	s_waitcnt vmcnt(0)
	s_barrier
	s_waitcnt lgkmcnt(2)
	v_mfma_f32_16x16x32_bf16 v[64:67], v[4:7], v[232:235], v[64:67]
	s_add_i32 m0, s8, 0x0
	ds_read_b128 v[224:227], v201 offset:55296
	global_load_lds_dwordx4 v140, s[98:99]
	v_exp_f32_e32 v183, v80
	v_cvt_pk_bf16_f32 v228, v203, v204
	v_mfma_f32_16x16x32_bf16 v[68:71], v[4:7], v[236:239], v[68:71]
	v_exp_f32_e32 v184, v81
	s_waitcnt lgkmcnt(2)
	v_mfma_f32_16x16x32_bf16 v[72:75], v[8:11], v[232:235], v[72:75]
	s_add_i32 m0, m0, 0x4000
	ds_read_b128 v[4:7], v201 offset:57344
	global_load_lds_dwordx4 v144, s[100:101]
	v_exp_f32_e32 v185, v82
	v_cvt_pk_bf16_f32 v229, v205, v206
	v_mfma_f32_16x16x32_bf16 v[76:79], v[8:11], v[236:239], v[76:79]
	v_exp_f32_e32 v186, v83
	s_waitcnt lgkmcnt(2)
	v_mfma_f32_16x16x32_bf16 v[48:51], v[12:15], v[232:235], v[48:51]
	s_add_i32 m0, m0, 0xffffc400
	ds_read_b128 v[8:11], v201 offset:59392
	global_load_lds_dwordx4 v142, s[98:99]
	v_exp_f32_e32 v187, v84
	v_cvt_pk_bf16_f32 v230, v211, v213
	v_mfma_f32_16x16x32_bf16 v[52:55], v[12:15], v[236:239], v[52:55]
	v_exp_f32_e32 v188, v85
	s_waitcnt lgkmcnt(2)
	v_mfma_f32_16x16x32_bf16 v[56:59], v[224:227], v[232:235], v[56:59]
	s_add_i32 m0, m0, 0x4000
	ds_read_b128 v[12:15], v201 offset:61440
	global_load_lds_dwordx4 v146, s[100:101]
	s_add_u32 s98, s98, 0x20000
	s_addc_u32 s99, s99, 0
	s_add_u32 s100, s100, 0x80
	s_addc_u32 s101, s101, 0
	v_exp_f32_e32 v189, v86
	v_cvt_pk_bf16_f32 v231, v214, v215
	v_mfma_f32_16x16x32_bf16 v[60:63], v[224:227], v[236:239], v[60:63]
	v_exp_f32_e32 v190, v87
	s_waitcnt lgkmcnt(2)
	v_mfma_f32_16x16x32_bf16 v[32:35], v[4:7], v[232:235], v[32:35]
	ds_read_b128 v[224:227], v201 offset:63488
	v_exp_f32_e32 v191, v88
	v_cvt_pk_bf16_f32 v240, v207, v208
	v_mfma_f32_16x16x32_bf16 v[36:39], v[4:7], v[236:239], v[36:39]
	v_exp_f32_e32 v192, v89
	s_waitcnt lgkmcnt(2)
	v_mfma_f32_16x16x32_bf16 v[40:43], v[8:11], v[232:235], v[40:43]
	ds_read_b128 v[4:7], v202 offset:49152
	v_exp_f32_e32 v193, v90
	v_cvt_pk_bf16_f32 v241, v209, v210
	v_mfma_f32_16x16x32_bf16 v[44:47], v[8:11], v[236:239], v[44:47]
	v_exp_f32_e32 v194, v91
	s_waitcnt lgkmcnt(2)
	v_mfma_f32_16x16x32_bf16 v[16:19], v[12:15], v[232:235], v[16:19]
	ds_read_b128 v[8:11], v202 offset:51200
	v_exp_f32_e32 v195, v92
	v_cvt_pk_bf16_f32 v242, v216, v217
	v_mfma_f32_16x16x32_bf16 v[20:23], v[12:15], v[236:239], v[20:23]
	v_exp_f32_e32 v196, v93
	s_waitcnt lgkmcnt(2)
	v_mfma_f32_16x16x32_bf16 v[24:27], v[224:227], v[232:235], v[24:27]
	ds_read_b128 v[12:15], v202 offset:53248
	v_exp_f32_e32 v197, v94
	v_cvt_pk_bf16_f32 v243, v218, v219
	v_mfma_f32_16x16x32_bf16 v[28:31], v[224:227], v[236:239], v[28:31]
	v_exp_f32_e32 v199, v95
	s_waitcnt lgkmcnt(2)
; #define SB() __builtin_amdgcn_sched_barrier(0)
; __device__ __forceinline__ void attn_unit(unsigned char* ws, const float* sub_g, LAS unsigned char* lds, int h, int qb, float negM, float lam) {
;     ...
;         bf16x8 F0 = FLOAD(0), F1 = FLOAD(1), F2;
;         SB();
;         F2 = FLOAD(2); s0 = __builtin_amdgcn_mfma_f32_32x32x16_bf16(F0, qf[0], negm, 0, 0, 0); ADD4(pa, 0); pw[0][0] = cvtpk(pa[0], pa[1]); SB();
;         F0 = FLOAD(3); s1 = __builtin_amdgcn_mfma_f32_32x32x16_bf16(F1, qf[0], negm, 0, 0, 0); ADD4(pa, 4); pw[0][1] = cvtpk(pa[2], pa[3]); SB();
;         F1 = FLOAD(4); s0 = __builtin_amdgcn_mfma_f32_32x32x16_bf16(F2, qf[1], s0, 0, 0, 0); ADD4(pa, 8); pw[0][2] = cvtpk(pa[4], pa[5]); SB();
;         F2 = FLOAD(5); s1 = __builtin_amdgcn_mfma_f32_32x32x16_bf16(F0, qf[1], s1, 0, 0, 0); ADD4(pa, 12); pw[0][3] = cvtpk(pa[6], pa[7]); SB();
;         F0 = FLOAD(6); s0 = __builtin_amdgcn_mfma_f32_32x32x16_bf16(F1, qf[2], s0, 0, 0, 0); ADD4(pb, 0); pw[1][0] = cvtpk(pa[8], pa[9]); SB();
;         F1 = FLOAD(7); s1 = __builtin_amdgcn_mfma_f32_32x32x16_bf16(F2, qf[2], s1, 0, 0, 0); ADD4(pb, 4); pw[1][1] = cvtpk(pa[10], pa[11]); SB();
;         F2 = FLOAD(8); s0 = __builtin_amdgcn_mfma_f32_32x32x16_bf16(F0, qf[3], s0, 0, 0, 0); ADD4(pb, 8); pw[1][2] = cvtpk(pa[12], pa[13]); SB();
;         F0 = FLOAD(9); s1 = __builtin_amdgcn_mfma_f32_32x32x16_bf16(F1, qf[3], s1, 0, 0, 0); ADD4(pb, 12); pw[1][3] = cvtpk(pa[14], pa[15]); SB();
;         F1 = FLOAD(10); o[0] = __builtin_amdgcn_mfma_f32_32x32x16_bf16(F2, __builtin_bit_cast(bf16x8, pw[0]), o[0], 0, 0, 0); pw[2][0] = cvtpk(pb[0], pb[1]); EXP2(s0, pa, 0); SB();
;         F2 = FLOAD(11); o[1] = __builtin_amdgcn_mfma_f32_32x32x16_bf16(F0, __builtin_bit_cast(bf16x8, pw[0]), o[1], 0, 0, 0); pw[2][1] = cvtpk(pb[2], pb[3]); EXP2(s0, pa, 2); SB();
;         F0 = FLOAD(12); o[2] = __builtin_amdgcn_mfma_f32_32x32x16_bf16(F1, __builtin_bit_cast(bf16x8, pw[0]), o[2], 0, 0, 0); pw[2][2] = cvtpk(pb[4], pb[5]); EXP2(s0, pa, 4); SB();
;         F1 = FLOAD(13); o[3] = __builtin_amdgcn_mfma_f32_32x32x16_bf16(F2, __builtin_bit_cast(bf16x8, pw[0]), o[3], 0, 0, 0); pw[2][3] = cvtpk(pb[6], pb[7]); EXP2(s0, pa, 6); SB();
;         F2 = FLOAD(14); o[0] = __builtin_amdgcn_mfma_f32_32x32x16_bf16(F0, __builtin_bit_cast(bf16x8, pw[1]), o[0], 0, 0, 0); pw[3][0] = cvtpk(pb[8], pb[9]); EXP2(s0, pa, 8); SB();
	v_mfma_f32_16x16x32_bf16 v[64:67], v[4:7], v[228:231], v[64:67]
	ds_read_b128 v[224:227], v202 offset:55296
	v_exp_f32_e32 v203, v96
	v_mfma_f32_16x16x32_bf16 v[68:71], v[4:7], v[240:243], v[68:71]
	v_exp_f32_e32 v204, v97
	s_waitcnt lgkmcnt(2)
	v_mfma_f32_16x16x32_bf16 v[72:75], v[8:11], v[228:231], v[72:75]
	ds_read_b128 v[4:7], v202 offset:57344
	v_exp_f32_e32 v205, v98
	v_mfma_f32_16x16x32_bf16 v[76:79], v[8:11], v[240:243], v[76:79]
	v_exp_f32_e32 v206, v99
	s_waitcnt lgkmcnt(2)
	v_mfma_f32_16x16x32_bf16 v[48:51], v[12:15], v[228:231], v[48:51]
	ds_read_b128 v[8:11], v202 offset:59392
	v_exp_f32_e32 v207, v100
	v_mfma_f32_16x16x32_bf16 v[52:55], v[12:15], v[240:243], v[52:55]
	v_exp_f32_e32 v208, v101
	s_waitcnt lgkmcnt(2)
	v_mfma_f32_16x16x32_bf16 v[56:59], v[224:227], v[228:231], v[56:59]
	ds_read_b128 v[12:15], v202 offset:61440
	v_exp_f32_e32 v209, v102
	v_mfma_f32_16x16x32_bf16 v[60:63], v[224:227], v[240:243], v[60:63]
	v_exp_f32_e32 v210, v103
	s_waitcnt lgkmcnt(2)
	v_mfma_f32_16x16x32_bf16 v[32:35], v[4:7], v[228:231], v[32:35]
	ds_read_b128 v[224:227], v202 offset:63488
	v_exp_f32_e32 v211, v104
	v_mfma_f32_16x16x32_bf16 v[36:39], v[4:7], v[240:243], v[36:39]
	v_exp_f32_e32 v213, v105
	s_waitcnt lgkmcnt(2)
	v_mfma_f32_16x16x32_bf16 v[40:43], v[8:11], v[228:231], v[40:43]
	ds_read_b128 v[4:7], v247 offset:32768
	v_exp_f32_e32 v214, v106
	v_mfma_f32_16x16x32_bf16 v[44:47], v[8:11], v[240:243], v[44:47]
	v_exp_f32_e32 v215, v107
	s_waitcnt lgkmcnt(2)
	v_mfma_f32_16x16x32_bf16 v[16:19], v[12:15], v[228:231], v[16:19]
	ds_read_b128 v[8:11], v248 offset:32768
	v_exp_f32_e32 v216, v108
	v_mfma_f32_16x16x32_bf16 v[20:23], v[12:15], v[240:243], v[20:23]
	v_exp_f32_e32 v217, v109
	s_waitcnt lgkmcnt(2)
	v_mfma_f32_16x16x32_bf16 v[24:27], v[224:227], v[228:231], v[24:27]
	ds_read_b128 v[12:15], v247 offset:34816
	v_exp_f32_e32 v218, v110
	v_mfma_f32_16x16x32_bf16 v[28:31], v[224:227], v[240:243], v[28:31]
	v_exp_f32_e32 v219, v111
	s_add_i32 s33, s33, 1
.Lattn_c3:
	s_waitcnt lgkmcnt(2)
	v_mfma_f32_16x16x32_bf16 v[80:83], v[4:7], v[112:115], v[0:3]
	ds_read_b128 v[224:227], v248 offset:34816
	v_add_f32_e32 v222, v222, v183
	v_add_f32_e32 v223, v223, v187
	v_cvt_pk_bf16_f32 v232, v183, v184
	v_mfma_f32_16x16x32_bf16 v[84:87], v[4:7], v[120:123], v[0:3]
	v_add_f32_e32 v222, v222, v184
	v_add_f32_e32 v223, v223, v188
	s_waitcnt lgkmcnt(2)
	v_mfma_f32_16x16x32_bf16 v[80:83], v[8:11], v[116:119], v[80:83]
	ds_read_b128 v[4:7], v247 offset:40960
	v_add_f32_e32 v222, v222, v185
	v_add_f32_e32 v223, v223, v189
	v_cvt_pk_bf16_f32 v233, v185, v186
	v_mfma_f32_16x16x32_bf16 v[84:87], v[8:11], v[124:127], v[84:87]
	v_add_f32_e32 v222, v222, v186
	v_add_f32_e32 v223, v223, v190
	s_waitcnt lgkmcnt(2)
	v_mfma_f32_16x16x32_bf16 v[88:91], v[12:15], v[112:115], v[0:3]
	ds_read_b128 v[8:11], v248 offset:40960
	v_add_f32_e32 v222, v222, v191
	v_add_f32_e32 v223, v223, v195
	v_cvt_pk_bf16_f32 v234, v191, v192
	v_mfma_f32_16x16x32_bf16 v[92:95], v[12:15], v[120:123], v[0:3]
	v_add_f32_e32 v222, v222, v192
	v_add_f32_e32 v223, v223, v196
	s_waitcnt lgkmcnt(2)
	v_mfma_f32_16x16x32_bf16 v[88:91], v[224:227], v[116:119], v[88:91]
	ds_read_b128 v[12:15], v247 offset:43008
	v_add_f32_e32 v222, v222, v193
	v_add_f32_e32 v223, v223, v197
	v_cvt_pk_bf16_f32 v235, v193, v194
	v_mfma_f32_16x16x32_bf16 v[92:95], v[224:227], v[124:127], v[92:95]
	v_add_f32_e32 v222, v222, v194
	v_add_f32_e32 v223, v223, v199
	s_waitcnt lgkmcnt(2)
	v_mfma_f32_16x16x32_bf16 v[96:99], v[4:7], v[112:115], v[0:3]
	ds_read_b128 v[224:227], v248 offset:43008
	v_add_f32_e32 v222, v222, v203
	v_add_f32_e32 v223, v223, v207
	v_cvt_pk_bf16_f32 v236, v187, v188
	v_mfma_f32_16x16x32_bf16 v[100:103], v[4:7], v[120:123], v[0:3]
	v_add_f32_e32 v222, v222, v204
	v_add_f32_e32 v223, v223, v208
	s_waitcnt lgkmcnt(2)
	v_mfma_f32_16x16x32_bf16 v[96:99], v[8:11], v[116:119], v[96:99]
	ds_read_b128 v[4:7], v249 offset:16384
	v_add_f32_e32 v222, v222, v205
	v_add_f32_e32 v223, v223, v209
	v_cvt_pk_bf16_f32 v237, v189, v190
	v_mfma_f32_16x16x32_bf16 v[100:103], v[8:11], v[124:127], v[100:103]
	v_add_f32_e32 v222, v222, v206
	v_add_f32_e32 v223, v223, v210
	s_waitcnt lgkmcnt(2)
	v_mfma_f32_16x16x32_bf16 v[104:107], v[12:15], v[112:115], v[0:3]
	ds_read_b128 v[8:11], v249 offset:18432
	v_add_f32_e32 v222, v222, v211
	v_add_f32_e32 v223, v223, v216
	v_cvt_pk_bf16_f32 v238, v195, v196
	v_mfma_f32_16x16x32_bf16 v[108:111], v[12:15], v[120:123], v[0:3]
	v_add_f32_e32 v222, v222, v213
	v_add_f32_e32 v223, v223, v217
	s_waitcnt lgkmcnt(2)
	v_mfma_f32_16x16x32_bf16 v[104:107], v[224:227], v[116:119], v[104:107]
	ds_read_b128 v[12:15], v249 offset:20480
	v_add_f32_e32 v222, v222, v214
	v_add_f32_e32 v223, v223, v218
	v_cvt_pk_bf16_f32 v239, v197, v199
	v_mfma_f32_16x16x32_bf16 v[108:111], v[224:227], v[124:127], v[108:111]
	v_add_f32_e32 v222, v222, v215
	v_add_f32_e32 v223, v223, v219
	s_waitcnt vmcnt(0)
	s_barrier
; #define SB() __builtin_amdgcn_sched_barrier(0)
; __device__ __forceinline__ void attn_unit(unsigned char* ws, const float* sub_g, LAS unsigned char* lds, int h, int qb, float negM, float lam) {
;     ...
;         bf16x8 F0 = FLOAD(0), F1 = FLOAD(1), F2;
;         SB();
;         F2 = FLOAD(2); s0 = __builtin_amdgcn_mfma_f32_32x32x16_bf16(F0, qf[0], negm, 0, 0, 0); ADD4(pa, 0); pw[0][0] = cvtpk(pa[0], pa[1]); SB();
;         F0 = FLOAD(3); s1 = __builtin_amdgcn_mfma_f32_32x32x16_bf16(F1, qf[0], negm, 0, 0, 0); ADD4(pa, 4); pw[0][1] = cvtpk(pa[2], pa[3]); SB();
;         F1 = FLOAD(4); s0 = __builtin_amdgcn_mfma_f32_32x32x16_bf16(F2, qf[1], s0, 0, 0, 0); ADD4(pa, 8); pw[0][2] = cvtpk(pa[4], pa[5]); SB();
;         F2 = FLOAD(5); s1 = __builtin_amdgcn_mfma_f32_32x32x16_bf16(F0, qf[1], s1, 0, 0, 0); ADD4(pa, 12); pw[0][3] = cvtpk(pa[6], pa[7]); SB();
;         F0 = FLOAD(6); s0 = __builtin_amdgcn_mfma_f32_32x32x16_bf16(F1, qf[2], s0, 0, 0, 0); ADD4(pb, 0); pw[1][0] = cvtpk(pa[8], pa[9]); SB();
;         F1 = FLOAD(7); s1 = __builtin_amdgcn_mfma_f32_32x32x16_bf16(F2, qf[2], s1, 0, 0, 0); ADD4(pb, 4); pw[1][1] = cvtpk(pa[10], pa[11]); SB();
;         F2 = FLOAD(8); s0 = __builtin_amdgcn_mfma_f32_32x32x16_bf16(F0, qf[3], s0, 0, 0, 0); ADD4(pb, 8); pw[1][2] = cvtpk(pa[12], pa[13]); SB();
;         F0 = FLOAD(9); s1 = __builtin_amdgcn_mfma_f32_32x32x16_bf16(F1, qf[3], s1, 0, 0, 0); ADD4(pb, 12); pw[1][3] = cvtpk(pa[14], pa[15]); SB();
;         F1 = FLOAD(10); o[0] = __builtin_amdgcn_mfma_f32_32x32x16_bf16(F2, __builtin_bit_cast(bf16x8, pw[0]), o[0], 0, 0, 0); pw[2][0] = cvtpk(pb[0], pb[1]); EXP2(s0, pa, 0); SB();
;         F2 = FLOAD(11); o[1] = __builtin_amdgcn_mfma_f32_32x32x16_bf16(F0, __builtin_bit_cast(bf16x8, pw[0]), o[1], 0, 0, 0); pw[2][1] = cvtpk(pb[2], pb[3]); EXP2(s0, pa, 2); SB();
;         F0 = FLOAD(12); o[2] = __builtin_amdgcn_mfma_f32_32x32x16_bf16(F1, __builtin_bit_cast(bf16x8, pw[0]), o[2], 0, 0, 0); pw[2][2] = cvtpk(pb[4], pb[5]); EXP2(s0, pa, 4); SB();
;         F1 = FLOAD(13); o[3] = __builtin_amdgcn_mfma_f32_32x32x16_bf16(F2, __builtin_bit_cast(bf16x8, pw[0]), o[3], 0, 0, 0); pw[2][3] = cvtpk(pb[6], pb[7]); EXP2(s0, pa, 6); SB();
;         F2 = FLOAD(14); o[0] = __builtin_amdgcn_mfma_f32_32x32x16_bf16(F0, __builtin_bit_cast(bf16x8, pw[1]), o[0], 0, 0, 0); pw[3][0] = cvtpk(pb[8], pb[9]); EXP2(s0, pa, 8); SB();
	s_waitcnt lgkmcnt(2)
	v_mfma_f32_16x16x32_bf16 v[64:67], v[4:7], v[232:235], v[64:67]
	s_add_i32 m0, s8, 0x8000
	ds_read_b128 v[224:227], v249 offset:22528
	global_load_lds_dwordx4 v140, s[98:99]
	v_exp_f32_e32 v183, v80
	v_cvt_pk_bf16_f32 v228, v203, v204
	v_mfma_f32_16x16x32_bf16 v[68:71], v[4:7], v[236:239], v[68:71]
	v_exp_f32_e32 v184, v81
	s_waitcnt lgkmcnt(2)
	v_mfma_f32_16x16x32_bf16 v[72:75], v[8:11], v[232:235], v[72:75]
	s_add_i32 m0, m0, 0x4000
	ds_read_b128 v[4:7], v249 offset:24576
	global_load_lds_dwordx4 v144, s[100:101]
	v_exp_f32_e32 v185, v82
	v_cvt_pk_bf16_f32 v229, v205, v206
	v_mfma_f32_16x16x32_bf16 v[76:79], v[8:11], v[236:239], v[76:79]
	v_exp_f32_e32 v186, v83
	s_waitcnt lgkmcnt(2)
	v_mfma_f32_16x16x32_bf16 v[48:51], v[12:15], v[232:235], v[48:51]
	s_add_i32 m0, m0, 0xffffc400
	ds_read_b128 v[8:11], v249 offset:26624
	global_load_lds_dwordx4 v142, s[98:99]
	v_exp_f32_e32 v187, v84
	v_cvt_pk_bf16_f32 v230, v211, v213
	v_mfma_f32_16x16x32_bf16 v[52:55], v[12:15], v[236:239], v[52:55]
	v_exp_f32_e32 v188, v85
	s_waitcnt lgkmcnt(2)
	v_mfma_f32_16x16x32_bf16 v[56:59], v[224:227], v[232:235], v[56:59]
	s_add_i32 m0, m0, 0x4000
	ds_read_b128 v[12:15], v249 offset:28672
	global_load_lds_dwordx4 v146, s[100:101]
	s_add_u32 s98, s98, 0x20000
	s_addc_u32 s99, s99, 0
	s_add_u32 s100, s100, 0x80
	s_addc_u32 s101, s101, 0
	v_exp_f32_e32 v189, v86
	v_cvt_pk_bf16_f32 v231, v214, v215
	v_mfma_f32_16x16x32_bf16 v[60:63], v[224:227], v[236:239], v[60:63]
	v_exp_f32_e32 v190, v87
	s_waitcnt lgkmcnt(2)
	v_mfma_f32_16x16x32_bf16 v[32:35], v[4:7], v[232:235], v[32:35]
	ds_read_b128 v[224:227], v249 offset:30720
	v_exp_f32_e32 v191, v88
	v_cvt_pk_bf16_f32 v240, v207, v208
	v_mfma_f32_16x16x32_bf16 v[36:39], v[4:7], v[236:239], v[36:39]
	v_exp_f32_e32 v192, v89
	s_waitcnt lgkmcnt(2)
	v_mfma_f32_16x16x32_bf16 v[40:43], v[8:11], v[232:235], v[40:43]
	ds_read_b128 v[4:7], v250 offset:16384
	v_exp_f32_e32 v193, v90
	v_cvt_pk_bf16_f32 v241, v209, v210
	v_mfma_f32_16x16x32_bf16 v[44:47], v[8:11], v[236:239], v[44:47]
	v_exp_f32_e32 v194, v91
	s_waitcnt lgkmcnt(2)
	v_mfma_f32_16x16x32_bf16 v[16:19], v[12:15], v[232:235], v[16:19]
	ds_read_b128 v[8:11], v250 offset:18432
	v_exp_f32_e32 v195, v92
	v_cvt_pk_bf16_f32 v242, v216, v217
	v_mfma_f32_16x16x32_bf16 v[20:23], v[12:15], v[236:239], v[20:23]
	v_exp_f32_e32 v196, v93
	s_waitcnt lgkmcnt(2)
	v_mfma_f32_16x16x32_bf16 v[24:27], v[224:227], v[232:235], v[24:27]
	ds_read_b128 v[12:15], v250 offset:20480
	v_exp_f32_e32 v197, v94
	v_cvt_pk_bf16_f32 v243, v218, v219
	v_mfma_f32_16x16x32_bf16 v[28:31], v[224:227], v[236:239], v[28:31]
	v_exp_f32_e32 v199, v95
	s_waitcnt lgkmcnt(2)
	v_mfma_f32_16x16x32_bf16 v[64:67], v[4:7], v[228:231], v[64:67]
	ds_read_b128 v[224:227], v250 offset:22528
	v_exp_f32_e32 v203, v96
	v_mfma_f32_16x16x32_bf16 v[68:71], v[4:7], v[240:243], v[68:71]
	v_exp_f32_e32 v204, v97
	s_waitcnt lgkmcnt(2)
	v_mfma_f32_16x16x32_bf16 v[72:75], v[8:11], v[228:231], v[72:75]
	ds_read_b128 v[4:7], v250 offset:24576
	v_exp_f32_e32 v205, v98
	v_mfma_f32_16x16x32_bf16 v[76:79], v[8:11], v[240:243], v[76:79]
	v_exp_f32_e32 v206, v99
	s_waitcnt lgkmcnt(2)
	v_mfma_f32_16x16x32_bf16 v[48:51], v[12:15], v[228:231], v[48:51]
	ds_read_b128 v[8:11], v250 offset:26624
	v_exp_f32_e32 v207, v100
	v_mfma_f32_16x16x32_bf16 v[52:55], v[12:15], v[240:243], v[52:55]
	v_exp_f32_e32 v208, v101
	s_waitcnt lgkmcnt(2)
	v_mfma_f32_16x16x32_bf16 v[56:59], v[224:227], v[228:231], v[56:59]
	ds_read_b128 v[12:15], v250 offset:28672
	v_exp_f32_e32 v209, v102
	v_mfma_f32_16x16x32_bf16 v[60:63], v[224:227], v[240:243], v[60:63]
	v_exp_f32_e32 v210, v103
	s_waitcnt lgkmcnt(2)
	v_mfma_f32_16x16x32_bf16 v[32:35], v[4:7], v[228:231], v[32:35]
	ds_read_b128 v[224:227], v250 offset:30720
	v_exp_f32_e32 v211, v104
	v_mfma_f32_16x16x32_bf16 v[36:39], v[4:7], v[240:243], v[36:39]
	v_exp_f32_e32 v213, v105
	s_waitcnt lgkmcnt(2)
	v_mfma_f32_16x16x32_bf16 v[40:43], v[8:11], v[228:231], v[40:43]
	ds_read_b128 v[4:7], v198
	v_exp_f32_e32 v214, v106
	v_mfma_f32_16x16x32_bf16 v[44:47], v[8:11], v[240:243], v[44:47]
	v_exp_f32_e32 v215, v107
	s_waitcnt lgkmcnt(2)
	v_mfma_f32_16x16x32_bf16 v[16:19], v[12:15], v[228:231], v[16:19]
	ds_read_b128 v[8:11], v200
	v_exp_f32_e32 v216, v108
	v_mfma_f32_16x16x32_bf16 v[20:23], v[12:15], v[240:243], v[20:23]
	v_exp_f32_e32 v217, v109
	s_waitcnt lgkmcnt(2)
	v_mfma_f32_16x16x32_bf16 v[24:27], v[224:227], v[228:231], v[24:27]
	ds_read_b128 v[12:15], v198 offset:2048
	v_exp_f32_e32 v218, v110
	v_mfma_f32_16x16x32_bf16 v[28:31], v[224:227], v[240:243], v[28:31]
	v_exp_f32_e32 v219, v111
	s_add_i32 s33, s33, 1
	s_cmpk_eq_i32 s33, 0x84
	s_cbranch_scc1 .Lattn_exit
; #define SB() __builtin_amdgcn_sched_barrier(0)
; __device__ __forceinline__ void attn_unit(unsigned char* ws, const float* sub_g, LAS unsigned char* lds, int h, int qb, float negM, float lam) {
;     ...
;         bf16x8 F0 = FLOAD(0), F1 = FLOAD(1), F2;
;         SB();
;         F2 = FLOAD(2); s0 = __builtin_amdgcn_mfma_f32_32x32x16_bf16(F0, qf[0], negm, 0, 0, 0); ADD4(pa, 0); pw[0][0] = cvtpk(pa[0], pa[1]); SB();
;         F0 = FLOAD(3); s1 = __builtin_amdgcn_mfma_f32_32x32x16_bf16(F1, qf[0], negm, 0, 0, 0); ADD4(pa, 4); pw[0][1] = cvtpk(pa[2], pa[3]); SB();
;         F1 = FLOAD(4); s0 = __builtin_amdgcn_mfma_f32_32x32x16_bf16(F2, qf[1], s0, 0, 0, 0); ADD4(pa, 8); pw[0][2] = cvtpk(pa[4], pa[5]); SB();
;         F2 = FLOAD(5); s1 = __builtin_amdgcn_mfma_f32_32x32x16_bf16(F0, qf[1], s1, 0, 0, 0); ADD4(pa, 12); pw[0][3] = cvtpk(pa[6], pa[7]); SB();
;         F0 = FLOAD(6); s0 = __builtin_amdgcn_mfma_f32_32x32x16_bf16(F1, qf[2], s0, 0, 0, 0); ADD4(pb, 0); pw[1][0] = cvtpk(pa[8], pa[9]); SB();
;         F1 = FLOAD(7); s1 = __builtin_amdgcn_mfma_f32_32x32x16_bf16(F2, qf[2], s1, 0, 0, 0); ADD4(pb, 4); pw[1][1] = cvtpk(pa[10], pa[11]); SB();
;         F2 = FLOAD(8); s0 = __builtin_amdgcn_mfma_f32_32x32x16_bf16(F0, qf[3], s0, 0, 0, 0); ADD4(pb, 8); pw[1][2] = cvtpk(pa[12], pa[13]); SB();
;         F0 = FLOAD(9); s1 = __builtin_amdgcn_mfma_f32_32x32x16_bf16(F1, qf[3], s1, 0, 0, 0); ADD4(pb, 12); pw[1][3] = cvtpk(pa[14], pa[15]); SB();
;         F1 = FLOAD(10); o[0] = __builtin_amdgcn_mfma_f32_32x32x16_bf16(F2, __builtin_bit_cast(bf16x8, pw[0]), o[0], 0, 0, 0); pw[2][0] = cvtpk(pb[0], pb[1]); EXP2(s0, pa, 0); SB();
;         F2 = FLOAD(11); o[1] = __builtin_amdgcn_mfma_f32_32x32x16_bf16(F0, __builtin_bit_cast(bf16x8, pw[0]), o[1], 0, 0, 0); pw[2][1] = cvtpk(pb[2], pb[3]); EXP2(s0, pa, 2); SB();
;         F0 = FLOAD(12); o[2] = __builtin_amdgcn_mfma_f32_32x32x16_bf16(F1, __builtin_bit_cast(bf16x8, pw[0]), o[2], 0, 0, 0); pw[2][2] = cvtpk(pb[4], pb[5]); EXP2(s0, pa, 4); SB();
;         F1 = FLOAD(13); o[3] = __builtin_amdgcn_mfma_f32_32x32x16_bf16(F2, __builtin_bit_cast(bf16x8, pw[0]), o[3], 0, 0, 0); pw[2][3] = cvtpk(pb[6], pb[7]); EXP2(s0, pa, 6); SB();
;         F2 = FLOAD(14); o[0] = __builtin_amdgcn_mfma_f32_32x32x16_bf16(F0, __builtin_bit_cast(bf16x8, pw[1]), o[0], 0, 0, 0); pw[3][0] = cvtpk(pb[8], pb[9]); EXP2(s0, pa, 8); SB();
.Lattn_c0:
	s_waitcnt lgkmcnt(2)
	v_mfma_f32_16x16x32_bf16 v[80:83], v[4:7], v[112:115], v[0:3]
	ds_read_b128 v[224:227], v200 offset:2048
	v_add_f32_e32 v222, v222, v183
	v_add_f32_e32 v223, v223, v187
	v_cvt_pk_bf16_f32 v232, v183, v184
	v_mfma_f32_16x16x32_bf16 v[84:87], v[4:7], v[120:123], v[0:3]
	v_add_f32_e32 v222, v222, v184
	v_add_f32_e32 v223, v223, v188
	s_waitcnt lgkmcnt(2)
	v_mfma_f32_16x16x32_bf16 v[80:83], v[8:11], v[116:119], v[80:83]
	ds_read_b128 v[4:7], v198 offset:8192
	v_add_f32_e32 v222, v222, v185
	v_add_f32_e32 v223, v223, v189
	v_cvt_pk_bf16_f32 v233, v185, v186
	v_mfma_f32_16x16x32_bf16 v[84:87], v[8:11], v[124:127], v[84:87]
	v_add_f32_e32 v222, v222, v186
	v_add_f32_e32 v223, v223, v190
	s_waitcnt lgkmcnt(2)
	v_mfma_f32_16x16x32_bf16 v[88:91], v[12:15], v[112:115], v[0:3]
	ds_read_b128 v[8:11], v200 offset:8192
	v_add_f32_e32 v222, v222, v191
	v_add_f32_e32 v223, v223, v195
	v_cvt_pk_bf16_f32 v234, v191, v192
	v_mfma_f32_16x16x32_bf16 v[92:95], v[12:15], v[120:123], v[0:3]
	v_add_f32_e32 v222, v222, v192
	v_add_f32_e32 v223, v223, v196
	s_waitcnt lgkmcnt(2)
	v_mfma_f32_16x16x32_bf16 v[88:91], v[224:227], v[116:119], v[88:91]
	ds_read_b128 v[12:15], v198 offset:10240
	v_add_f32_e32 v222, v222, v193
	v_add_f32_e32 v223, v223, v197
	v_cvt_pk_bf16_f32 v235, v193, v194
	v_mfma_f32_16x16x32_bf16 v[92:95], v[224:227], v[124:127], v[92:95]
	v_add_f32_e32 v222, v222, v194
	v_add_f32_e32 v223, v223, v199
	s_waitcnt lgkmcnt(2)
	v_mfma_f32_16x16x32_bf16 v[96:99], v[4:7], v[112:115], v[0:3]
	ds_read_b128 v[224:227], v200 offset:10240
	v_add_f32_e32 v222, v222, v203
	v_add_f32_e32 v223, v223, v207
	v_cvt_pk_bf16_f32 v236, v187, v188
	v_mfma_f32_16x16x32_bf16 v[100:103], v[4:7], v[120:123], v[0:3]
	v_add_f32_e32 v222, v222, v204
	v_add_f32_e32 v223, v223, v208
	s_waitcnt lgkmcnt(2)
	v_mfma_f32_16x16x32_bf16 v[96:99], v[8:11], v[116:119], v[96:99]
	ds_read_b128 v[4:7], v249 offset:49152
	v_add_f32_e32 v222, v222, v205
	v_add_f32_e32 v223, v223, v209
	v_cvt_pk_bf16_f32 v237, v189, v190
	v_mfma_f32_16x16x32_bf16 v[100:103], v[8:11], v[124:127], v[100:103]
	v_add_f32_e32 v222, v222, v206
	v_add_f32_e32 v223, v223, v210
	s_waitcnt lgkmcnt(2)
	v_mfma_f32_16x16x32_bf16 v[104:107], v[12:15], v[112:115], v[0:3]
	ds_read_b128 v[8:11], v249 offset:51200
	v_add_f32_e32 v222, v222, v211
	v_add_f32_e32 v223, v223, v216
	v_cvt_pk_bf16_f32 v238, v195, v196
	v_mfma_f32_16x16x32_bf16 v[108:111], v[12:15], v[120:123], v[0:3]
	v_add_f32_e32 v222, v222, v213
	v_add_f32_e32 v223, v223, v217
	s_waitcnt lgkmcnt(2)
	v_mfma_f32_16x16x32_bf16 v[104:107], v[224:227], v[116:119], v[104:107]
	ds_read_b128 v[12:15], v249 offset:53248
	v_add_f32_e32 v222, v222, v214
	v_add_f32_e32 v223, v223, v218
	v_cvt_pk_bf16_f32 v239, v197, v199
	v_mfma_f32_16x16x32_bf16 v[108:111], v[224:227], v[124:127], v[108:111]
	v_add_f32_e32 v222, v222, v215
	v_add_f32_e32 v223, v223, v219
	s_waitcnt vmcnt(0)
	s_barrier
	s_waitcnt lgkmcnt(2)
	v_mfma_f32_16x16x32_bf16 v[64:67], v[4:7], v[232:235], v[64:67]
	s_add_i32 m0, s8, 0x10000
	ds_read_b128 v[224:227], v249 offset:55296
	global_load_lds_dwordx4 v140, s[98:99]
	v_exp_f32_e32 v183, v80
	v_cvt_pk_bf16_f32 v228, v203, v204
	v_mfma_f32_16x16x32_bf16 v[68:71], v[4:7], v[236:239], v[68:71]
	v_exp_f32_e32 v184, v81
	s_waitcnt lgkmcnt(2)
	v_mfma_f32_16x16x32_bf16 v[72:75], v[8:11], v[232:235], v[72:75]
	s_add_i32 m0, m0, 0x4000
	ds_read_b128 v[4:7], v249 offset:57344
	global_load_lds_dwordx4 v144, s[100:101]
	v_exp_f32_e32 v185, v82
	v_cvt_pk_bf16_f32 v229, v205, v206
	v_mfma_f32_16x16x32_bf16 v[76:79], v[8:11], v[236:239], v[76:79]
	v_exp_f32_e32 v186, v83
	s_waitcnt lgkmcnt(2)
	v_mfma_f32_16x16x32_bf16 v[48:51], v[12:15], v[232:235], v[48:51]
	s_add_i32 m0, m0, 0xffffc400
	ds_read_b128 v[8:11], v249 offset:59392
	global_load_lds_dwordx4 v142, s[98:99]
	v_exp_f32_e32 v187, v84
	v_cvt_pk_bf16_f32 v230, v211, v213
	v_mfma_f32_16x16x32_bf16 v[52:55], v[12:15], v[236:239], v[52:55]
	v_exp_f32_e32 v188, v85
	s_waitcnt lgkmcnt(2)
	v_mfma_f32_16x16x32_bf16 v[56:59], v[224:227], v[232:235], v[56:59]
	s_add_i32 m0, m0, 0x4000
	ds_read_b128 v[12:15], v249 offset:61440
	global_load_lds_dwordx4 v146, s[100:101]
	s_add_u32 s98, s98, 0x20000
	s_addc_u32 s99, s99, 0
	s_add_u32 s100, s100, 0x80
	s_addc_u32 s101, s101, 0
	v_exp_f32_e32 v189, v86
	v_cvt_pk_bf16_f32 v231, v214, v215
	v_mfma_f32_16x16x32_bf16 v[60:63], v[224:227], v[236:239], v[60:63]
	v_exp_f32_e32 v190, v87
	s_waitcnt lgkmcnt(2)
	v_mfma_f32_16x16x32_bf16 v[32:35], v[4:7], v[232:235], v[32:35]
	ds_read_b128 v[224:227], v249 offset:63488
	v_exp_f32_e32 v191, v88
	v_cvt_pk_bf16_f32 v240, v207, v208
	v_mfma_f32_16x16x32_bf16 v[36:39], v[4:7], v[236:239], v[36:39]
	v_exp_f32_e32 v192, v89
	s_waitcnt lgkmcnt(2)
	v_mfma_f32_16x16x32_bf16 v[40:43], v[8:11], v[232:235], v[40:43]
	ds_read_b128 v[4:7], v250 offset:49152
	v_exp_f32_e32 v193, v90
	v_cvt_pk_bf16_f32 v241, v209, v210
	v_mfma_f32_16x16x32_bf16 v[44:47], v[8:11], v[236:239], v[44:47]
	v_exp_f32_e32 v194, v91
	s_waitcnt lgkmcnt(2)
	v_mfma_f32_16x16x32_bf16 v[16:19], v[12:15], v[232:235], v[16:19]
	ds_read_b128 v[8:11], v250 offset:51200
	v_exp_f32_e32 v195, v92
	v_cvt_pk_bf16_f32 v242, v216, v217
	v_mfma_f32_16x16x32_bf16 v[20:23], v[12:15], v[236:239], v[20:23]
	v_exp_f32_e32 v196, v93
	s_waitcnt lgkmcnt(2)
	v_mfma_f32_16x16x32_bf16 v[24:27], v[224:227], v[232:235], v[24:27]
	ds_read_b128 v[12:15], v250 offset:53248
	v_exp_f32_e32 v197, v94
	v_cvt_pk_bf16_f32 v243, v218, v219
	v_mfma_f32_16x16x32_bf16 v[28:31], v[224:227], v[236:239], v[28:31]
	v_exp_f32_e32 v199, v95
	s_waitcnt lgkmcnt(2)
; __device__ __forceinline__ void attn_unit(unsigned char* ws, const float* sub_g, LAS unsigned char* lds, int h, int qb, float negM, float lam) {
;     ...
;         F1 = FLOAD(10); o[0] = __builtin_amdgcn_mfma_f32_32x32x16_bf16(F2, __builtin_bit_cast(bf16x8, pw[0]), o[0], 0, 0, 0); pw[2][0] = cvtpk(pb[0], pb[1]); EXP2(s0, pa, 0); SB();
;         F2 = FLOAD(11); o[1] = __builtin_amdgcn_mfma_f32_32x32x16_bf16(F0, __builtin_bit_cast(bf16x8, pw[0]), o[1], 0, 0, 0); pw[2][1] = cvtpk(pb[2], pb[3]); EXP2(s0, pa, 2); SB();
;         F0 = FLOAD(12); o[2] = __builtin_amdgcn_mfma_f32_32x32x16_bf16(F1, __builtin_bit_cast(bf16x8, pw[0]), o[2], 0, 0, 0); pw[2][2] = cvtpk(pb[4], pb[5]); EXP2(s0, pa, 4); SB();
;         F1 = FLOAD(13); o[3] = __builtin_amdgcn_mfma_f32_32x32x16_bf16(F2, __builtin_bit_cast(bf16x8, pw[0]), o[3], 0, 0, 0); pw[2][3] = cvtpk(pb[6], pb[7]); EXP2(s0, pa, 6); SB();
;         F2 = FLOAD(14); o[0] = __builtin_amdgcn_mfma_f32_32x32x16_bf16(F0, __builtin_bit_cast(bf16x8, pw[1]), o[0], 0, 0, 0); pw[3][0] = cvtpk(pb[8], pb[9]); EXP2(s0, pa, 8); SB();
;         F0 = FLOAD(15); o[1] = __builtin_amdgcn_mfma_f32_32x32x16_bf16(F1, __builtin_bit_cast(bf16x8, pw[1]), o[1], 0, 0, 0); pw[3][1] = cvtpk(pb[10], pb[11]); EXP2(s0, pa, 10); SB();
;         F1 = FLOAD(16); o[2] = __builtin_amdgcn_mfma_f32_32x32x16_bf16(F2, __builtin_bit_cast(bf16x8, pw[1]), o[2], 0, 0, 0); pw[3][2] = cvtpk(pb[12], pb[13]); EXP2(s0, pa, 12); SB();
;         F2 = FLOAD(17); o[3] = __builtin_amdgcn_mfma_f32_32x32x16_bf16(F0, __builtin_bit_cast(bf16x8, pw[1]), o[3], 0, 0, 0); pw[3][3] = cvtpk(pb[14], pb[15]); EXP2(s0, pa, 14); SB();
;         F0 = FLOAD(18); o[0] = __builtin_amdgcn_mfma_f32_32x32x16_bf16(F1, __builtin_bit_cast(bf16x8, pw[2]), o[0], 0, 0, 0); EXP2(s1, pb, 0); SB();
;         F1 = FLOAD(19); o[1] = __builtin_amdgcn_mfma_f32_32x32x16_bf16(F2, __builtin_bit_cast(bf16x8, pw[2]), o[1], 0, 0, 0); EXP2(s1, pb, 2); SB();
;         F2 = FLOAD(20); o[2] = __builtin_amdgcn_mfma_f32_32x32x16_bf16(F0, __builtin_bit_cast(bf16x8, pw[2]), o[2], 0, 0, 0); EXP2(s1, pb, 4); SB();
;         F0 = FLOAD(21); o[3] = __builtin_amdgcn_mfma_f32_32x32x16_bf16(F1, __builtin_bit_cast(bf16x8, pw[2]), o[3], 0, 0, 0); EXP2(s1, pb, 6); SB();
;         F1 = FLOAD(22); o[0] = __builtin_amdgcn_mfma_f32_32x32x16_bf16(F2, __builtin_bit_cast(bf16x8, pw[3]), o[0], 0, 0, 0); EXP2(s1, pb, 8); SB();
	v_mfma_f32_16x16x32_bf16 v[64:67], v[4:7], v[228:231], v[64:67]
	ds_read_b128 v[224:227], v250 offset:55296
	v_exp_f32_e32 v203, v96
	v_mfma_f32_16x16x32_bf16 v[68:71], v[4:7], v[240:243], v[68:71]
	v_exp_f32_e32 v204, v97
	s_waitcnt lgkmcnt(2)
	v_mfma_f32_16x16x32_bf16 v[72:75], v[8:11], v[228:231], v[72:75]
	ds_read_b128 v[4:7], v250 offset:57344
	v_exp_f32_e32 v205, v98
	v_mfma_f32_16x16x32_bf16 v[76:79], v[8:11], v[240:243], v[76:79]
	v_exp_f32_e32 v206, v99
	s_waitcnt lgkmcnt(2)
	v_mfma_f32_16x16x32_bf16 v[48:51], v[12:15], v[228:231], v[48:51]
	ds_read_b128 v[8:11], v250 offset:59392
	v_exp_f32_e32 v207, v100
	v_mfma_f32_16x16x32_bf16 v[52:55], v[12:15], v[240:243], v[52:55]
	v_exp_f32_e32 v208, v101
	s_waitcnt lgkmcnt(2)
	v_mfma_f32_16x16x32_bf16 v[56:59], v[224:227], v[228:231], v[56:59]
	ds_read_b128 v[12:15], v250 offset:61440
	v_exp_f32_e32 v209, v102
	v_mfma_f32_16x16x32_bf16 v[60:63], v[224:227], v[240:243], v[60:63]
	v_exp_f32_e32 v210, v103
	s_waitcnt lgkmcnt(2)
	v_mfma_f32_16x16x32_bf16 v[32:35], v[4:7], v[228:231], v[32:35]
	ds_read_b128 v[224:227], v250 offset:63488
	v_exp_f32_e32 v211, v104
	v_mfma_f32_16x16x32_bf16 v[36:39], v[4:7], v[240:243], v[36:39]
	v_exp_f32_e32 v213, v105
	s_waitcnt lgkmcnt(2)
	v_mfma_f32_16x16x32_bf16 v[40:43], v[8:11], v[228:231], v[40:43]
	ds_read_b128 v[4:7], v198 offset:32768
	v_exp_f32_e32 v214, v106
	v_mfma_f32_16x16x32_bf16 v[44:47], v[8:11], v[240:243], v[44:47]
	v_exp_f32_e32 v215, v107
	s_waitcnt lgkmcnt(2)
	v_mfma_f32_16x16x32_bf16 v[16:19], v[12:15], v[228:231], v[16:19]
	ds_read_b128 v[8:11], v200 offset:32768
	v_exp_f32_e32 v216, v108
	v_mfma_f32_16x16x32_bf16 v[20:23], v[12:15], v[240:243], v[20:23]
	v_exp_f32_e32 v217, v109
	s_waitcnt lgkmcnt(2)
	v_mfma_f32_16x16x32_bf16 v[24:27], v[224:227], v[228:231], v[24:27]
	ds_read_b128 v[12:15], v198 offset:34816
	v_exp_f32_e32 v218, v110
	v_mfma_f32_16x16x32_bf16 v[28:31], v[224:227], v[240:243], v[28:31]
	v_exp_f32_e32 v219, v111
	s_add_i32 s33, s33, 1
	s_branch .Lattn_c1
.Lattn_exit:
	s_waitcnt lgkmcnt(0)
	ds_read_b128 v[80:83], v249 offset:49152
	ds_read_b128 v[84:87], v249 offset:51200
	ds_read_b128 v[88:91], v249 offset:53248
	ds_read_b128 v[92:95], v249 offset:55296
	ds_read_b128 v[96:99], v249 offset:57344
	ds_read_b128 v[100:103], v249 offset:59392
	ds_read_b128 v[104:107], v249 offset:61440
	ds_read_b128 v[108:111], v249 offset:63488
	v_add_f32_e32 v222, v222, v183
	v_add_f32_e32 v223, v223, v187
	v_add_f32_e32 v222, v222, v184
	v_add_f32_e32 v223, v223, v188
	v_add_f32_e32 v222, v222, v185
	v_add_f32_e32 v223, v223, v189
	v_add_f32_e32 v222, v222, v186
	v_add_f32_e32 v223, v223, v190
	v_add_f32_e32 v222, v222, v191
	v_add_f32_e32 v223, v223, v195
	v_add_f32_e32 v222, v222, v192
	v_add_f32_e32 v223, v223, v196
	v_add_f32_e32 v222, v222, v193
	v_add_f32_e32 v223, v223, v197
	v_add_f32_e32 v222, v222, v194
	v_add_f32_e32 v223, v223, v199
	v_add_f32_e32 v222, v222, v203
	v_add_f32_e32 v223, v223, v207
	v_add_f32_e32 v222, v222, v204
	v_add_f32_e32 v223, v223, v208
	v_add_f32_e32 v222, v222, v205
	v_add_f32_e32 v223, v223, v209
	v_add_f32_e32 v222, v222, v206
	v_add_f32_e32 v223, v223, v210
	v_add_f32_e32 v222, v222, v211
	v_add_f32_e32 v223, v223, v216
	v_add_f32_e32 v222, v222, v213
	v_add_f32_e32 v223, v223, v217
	v_add_f32_e32 v222, v222, v214
	v_add_f32_e32 v223, v223, v218
	v_add_f32_e32 v222, v222, v215
	v_add_f32_e32 v223, v223, v219
	v_cvt_pk_bf16_f32 v232, v183, v184
	v_cvt_pk_bf16_f32 v233, v185, v186
	v_cvt_pk_bf16_f32 v234, v191, v192
	v_cvt_pk_bf16_f32 v235, v193, v194
	v_cvt_pk_bf16_f32 v236, v187, v188
	v_cvt_pk_bf16_f32 v237, v189, v190
	v_cvt_pk_bf16_f32 v238, v195, v196
	v_cvt_pk_bf16_f32 v239, v197, v199
	v_cvt_pk_bf16_f32 v228, v203, v204
	v_cvt_pk_bf16_f32 v229, v205, v206
	v_cvt_pk_bf16_f32 v230, v211, v213
	v_cvt_pk_bf16_f32 v231, v214, v215
	v_cvt_pk_bf16_f32 v240, v207, v208
	v_cvt_pk_bf16_f32 v241, v209, v210
	v_cvt_pk_bf16_f32 v242, v216, v217
	v_cvt_pk_bf16_f32 v243, v218, v219
	s_lshl_b32 s8, s29, 14
	s_add_i32 s29, s8, 0
	s_waitcnt lgkmcnt(7)
	v_mfma_f32_16x16x32_bf16 v[64:67], v[80:83], v[232:235], v[64:67]
	v_mfma_f32_16x16x32_bf16 v[68:71], v[80:83], v[236:239], v[68:71]
	s_waitcnt lgkmcnt(6)
	v_mfma_f32_16x16x32_bf16 v[72:75], v[84:87], v[232:235], v[72:75]
	v_mfma_f32_16x16x32_bf16 v[76:79], v[84:87], v[236:239], v[76:79]
	s_waitcnt lgkmcnt(5)
	v_mfma_f32_16x16x32_bf16 v[48:51], v[88:91], v[232:235], v[48:51]
	v_mfma_f32_16x16x32_bf16 v[52:55], v[88:91], v[236:239], v[52:55]
	s_waitcnt lgkmcnt(4)
	v_mfma_f32_16x16x32_bf16 v[56:59], v[92:95], v[232:235], v[56:59]
	v_mfma_f32_16x16x32_bf16 v[60:63], v[92:95], v[236:239], v[60:63]
	s_waitcnt lgkmcnt(3)
	v_mfma_f32_16x16x32_bf16 v[32:35], v[96:99], v[232:235], v[32:35]
	v_mfma_f32_16x16x32_bf16 v[36:39], v[96:99], v[236:239], v[36:39]
	s_waitcnt lgkmcnt(2)
	v_mfma_f32_16x16x32_bf16 v[40:43], v[100:103], v[232:235], v[40:43]
	v_mfma_f32_16x16x32_bf16 v[44:47], v[100:103], v[236:239], v[44:47]
	s_waitcnt lgkmcnt(1)
	v_mfma_f32_16x16x32_bf16 v[16:19], v[104:107], v[232:235], v[16:19]
	v_mfma_f32_16x16x32_bf16 v[20:23], v[104:107], v[236:239], v[20:23]
	s_waitcnt lgkmcnt(0)
	v_mfma_f32_16x16x32_bf16 v[24:27], v[108:111], v[232:235], v[24:27]
	v_mfma_f32_16x16x32_bf16 v[28:31], v[108:111], v[236:239], v[28:31]
	ds_read_b128 v[4:7], v250 offset:49152
	ds_read_b128 v[8:11], v250 offset:51200
	ds_read_b128 v[12:15], v250 offset:53248
	ds_read_b128 v[224:227], v250 offset:55296
	ds_read_b128 v[112:115], v250 offset:57344
	ds_read_b128 v[116:119], v250 offset:59392
	ds_read_b128 v[120:123], v250 offset:61440
	ds_read_b128 v[124:127], v250 offset:63488
	s_waitcnt lgkmcnt(7)
	v_mfma_f32_16x16x32_bf16 v[64:67], v[4:7], v[228:231], v[64:67]
	v_mfma_f32_16x16x32_bf16 v[68:71], v[4:7], v[240:243], v[68:71]
	s_waitcnt lgkmcnt(6)
	v_mfma_f32_16x16x32_bf16 v[72:75], v[8:11], v[228:231], v[72:75]
	v_mfma_f32_16x16x32_bf16 v[76:79], v[8:11], v[240:243], v[76:79]
	s_waitcnt lgkmcnt(5)
	v_mfma_f32_16x16x32_bf16 v[48:51], v[12:15], v[228:231], v[48:51]
	v_mfma_f32_16x16x32_bf16 v[52:55], v[12:15], v[240:243], v[52:55]
	s_waitcnt lgkmcnt(4)
	v_mfma_f32_16x16x32_bf16 v[56:59], v[224:227], v[228:231], v[56:59]
	v_mfma_f32_16x16x32_bf16 v[60:63], v[224:227], v[240:243], v[60:63]
	s_waitcnt lgkmcnt(3)
	v_mfma_f32_16x16x32_bf16 v[32:35], v[112:115], v[228:231], v[32:35]
	v_mfma_f32_16x16x32_bf16 v[36:39], v[112:115], v[240:243], v[36:39]
	s_waitcnt lgkmcnt(2)
	v_mfma_f32_16x16x32_bf16 v[40:43], v[116:119], v[228:231], v[40:43]
	v_mfma_f32_16x16x32_bf16 v[44:47], v[116:119], v[240:243], v[44:47]
	s_waitcnt lgkmcnt(1)
	v_mfma_f32_16x16x32_bf16 v[16:19], v[120:123], v[228:231], v[16:19]
	v_mfma_f32_16x16x32_bf16 v[20:23], v[120:123], v[240:243], v[20:23]
	s_waitcnt lgkmcnt(0)
	v_mfma_f32_16x16x32_bf16 v[24:27], v[124:127], v[228:231], v[24:27]
	v_mfma_f32_16x16x32_bf16 v[28:31], v[124:127], v[240:243], v[28:31]
	s_waitcnt vmcnt(0)
	s_barrier
; #define LAS __attribute__((address_space(3)))
; __device__ __forceinline__ void attn_unit(unsigned char* ws, const float* sub_g, LAS unsigned char* lds, int h, int qb, float negM, float lam) {
;     ...
;     float l = l0 + l1;
;     ...
;     asm volatile("s_waitcnt vmcnt(0) lgkmcnt(0)" ::: "memory");
;     __builtin_amdgcn_s_barrier();
;     l += __shfl_xor(l, 32);
;     const float inv = 1.0f / l;
;     LAS float* xw = (LAS float*)(lds + AT_XOFF + wq * 16384);
;     if (map == 1) {
;         const float f = inv * lam;
; #pragma unroll
;         for (int b = 0; b < 4; ++b)
; #pragma unroll
;             for (int r = 0; r < 16; ++r) xw[(b * 16 + r) * 64 + lane] = o[b][r] * f;
	v_mov_b32_e32 v251, v222
	v_mov_b32_e32 v252, v223
	s_nop 1
	v_permlane16_swap_b32_e32 v251, v222
	v_permlane16_swap_b32_e32 v252, v223
	v_add_f32_e32 v222, v222, v251
	v_add_f32_e32 v223, v223, v252
	v_mov_b32_e32 v251, v222
	v_mov_b32_e32 v252, v223
	s_nop 1
	v_permlane32_swap_b32_e32 v251, v222
	v_permlane32_swap_b32_e32 v252, v223
	v_add_f32_e32 v222, v222, v251
	v_add_f32_e32 v223, v223, v252
	v_and_b32_e32 v251, 16, v220
	v_cmp_ne_u32_e32 vcc, 0, v251
	v_cndmask_b32_e32 v88, v222, v223, vcc
	s_nop 7
	v_permlane16_swap_b32_e32 v64, v68
	v_permlane16_swap_b32_e32 v65, v69
	v_permlane16_swap_b32_e32 v66, v70
	v_permlane16_swap_b32_e32 v67, v71
	v_permlane16_swap_b32_e32 v72, v76
	v_permlane16_swap_b32_e32 v73, v77
	v_permlane16_swap_b32_e32 v74, v78
	v_permlane16_swap_b32_e32 v75, v79
	v_permlane16_swap_b32_e32 v48, v52
	v_permlane16_swap_b32_e32 v49, v53
	v_permlane16_swap_b32_e32 v50, v54
	v_permlane16_swap_b32_e32 v51, v55
	v_permlane16_swap_b32_e32 v56, v60
	v_permlane16_swap_b32_e32 v57, v61
	v_permlane16_swap_b32_e32 v58, v62
	v_permlane16_swap_b32_e32 v59, v63
	v_permlane16_swap_b32_e32 v32, v36
	v_permlane16_swap_b32_e32 v33, v37
	v_permlane16_swap_b32_e32 v34, v38
	v_permlane16_swap_b32_e32 v35, v39
	v_permlane16_swap_b32_e32 v40, v44
	v_permlane16_swap_b32_e32 v41, v45
	v_permlane16_swap_b32_e32 v42, v46
	v_permlane16_swap_b32_e32 v43, v47
	v_permlane16_swap_b32_e32 v16, v20
	v_permlane16_swap_b32_e32 v17, v21
	v_permlane16_swap_b32_e32 v18, v22
	v_permlane16_swap_b32_e32 v19, v23
	v_permlane16_swap_b32_e32 v24, v28
	v_permlane16_swap_b32_e32 v25, v29
	v_permlane16_swap_b32_e32 v26, v30
	v_permlane16_swap_b32_e32 v27, v31
	v_permlane32_swap_b32_e32 v64, v68
	v_permlane32_swap_b32_e32 v65, v69
	v_permlane32_swap_b32_e32 v66, v70
	v_permlane32_swap_b32_e32 v67, v71
	v_permlane32_swap_b32_e32 v72, v76
	v_permlane32_swap_b32_e32 v73, v77
	v_permlane32_swap_b32_e32 v74, v78
	v_permlane32_swap_b32_e32 v75, v79
	v_permlane32_swap_b32_e32 v48, v52
	v_permlane32_swap_b32_e32 v49, v53
	v_permlane32_swap_b32_e32 v50, v54
	v_permlane32_swap_b32_e32 v51, v55
	v_permlane32_swap_b32_e32 v56, v60
	v_permlane32_swap_b32_e32 v57, v61
	v_permlane32_swap_b32_e32 v58, v62
	v_permlane32_swap_b32_e32 v59, v63
	v_permlane32_swap_b32_e32 v32, v36
	v_permlane32_swap_b32_e32 v33, v37
	v_permlane32_swap_b32_e32 v34, v38
	v_permlane32_swap_b32_e32 v35, v39
	v_permlane32_swap_b32_e32 v40, v44
	v_permlane32_swap_b32_e32 v41, v45
	v_permlane32_swap_b32_e32 v42, v46
	v_permlane32_swap_b32_e32 v43, v47
	v_permlane32_swap_b32_e32 v16, v20
	v_permlane32_swap_b32_e32 v17, v21
	v_permlane32_swap_b32_e32 v18, v22
	v_permlane32_swap_b32_e32 v19, v23
	v_permlane32_swap_b32_e32 v24, v28
	v_permlane32_swap_b32_e32 v25, v29
	v_permlane32_swap_b32_e32 v26, v30
	v_permlane32_swap_b32_e32 v27, v31
	v_div_scale_f32 v89, s[30:31], v88, v88, 1.0
	v_rcp_f32_e32 v90, v89
	s_nop 1
	v_fma_f32 v80, -v89, v90, 1.0
	v_fmac_f32_e32 v90, v80, v90
	v_div_scale_f32 v80, vcc, 1.0, v88, 1.0
	v_mul_f32_e32 v81, v80, v90
	v_fma_f32 v82, -v89, v81, v80
	v_fmac_f32_e32 v81, v82, v90
	s_nop 1
	v_fma_f32 v80, -v89, v81, v80
	s_nop 1
	v_div_fmas_f32 v80, v80, v90, v81
	v_div_fixup_f32 v90, v80, v88, 1.0
	v_lshl_add_u32 v80, v221, 2, s29
	s_cmp_eq_u32 s28, 1
	s_cbranch_scc0 .LBB0_836
	v_mul_f32_e32 v81, v129, v90
	v_mul_f32_e32 v82, v64, v81
	v_mul_f32_e32 v83, v65, v81
	ds_write2st64_b32 v80, v82, v83 offset1:1
	v_mul_f32_e32 v82, v66, v81
	v_mul_f32_e32 v83, v67, v81
	ds_write2st64_b32 v80, v82, v83 offset0:2 offset1:3
	v_mul_f32_e32 v82, v68, v81
	v_mul_f32_e32 v83, v69, v81
	ds_write2st64_b32 v80, v82, v83 offset0:4 offset1:5
	v_mul_f32_e32 v82, v70, v81
	v_mul_f32_e32 v83, v71, v81
	ds_write2st64_b32 v80, v82, v83 offset0:6 offset1:7
	v_mul_f32_e32 v82, v72, v81
	v_mul_f32_e32 v83, v73, v81
	ds_write2st64_b32 v80, v82, v83 offset0:8 offset1:9
	v_mul_f32_e32 v82, v74, v81
	v_mul_f32_e32 v83, v75, v81
	ds_write2st64_b32 v80, v82, v83 offset0:10 offset1:11
	v_mul_f32_e32 v82, v76, v81
	v_mul_f32_e32 v83, v77, v81
	ds_write2st64_b32 v80, v82, v83 offset0:12 offset1:13
	v_mul_f32_e32 v82, v78, v81
	v_mul_f32_e32 v83, v79, v81
	ds_write2st64_b32 v80, v82, v83 offset0:14 offset1:15
	v_mul_f32_e32 v82, v48, v81
	v_mul_f32_e32 v83, v49, v81
	ds_write2st64_b32 v80, v82, v83 offset0:16 offset1:17
	v_mul_f32_e32 v82, v50, v81
	v_mul_f32_e32 v83, v51, v81
	ds_write2st64_b32 v80, v82, v83 offset0:18 offset1:19
	v_mul_f32_e32 v82, v52, v81
	v_mul_f32_e32 v83, v53, v81
	ds_write2st64_b32 v80, v82, v83 offset0:20 offset1:21
	v_mul_f32_e32 v82, v54, v81
	v_mul_f32_e32 v83, v55, v81
	ds_write2st64_b32 v80, v82, v83 offset0:22 offset1:23
	v_mul_f32_e32 v82, v56, v81
	v_mul_f32_e32 v83, v57, v81
	ds_write2st64_b32 v80, v82, v83 offset0:24 offset1:25
	v_mul_f32_e32 v82, v58, v81
	v_mul_f32_e32 v83, v59, v81
	ds_write2st64_b32 v80, v82, v83 offset0:26 offset1:27
	v_mul_f32_e32 v82, v60, v81
	v_mul_f32_e32 v83, v61, v81
	ds_write2st64_b32 v80, v82, v83 offset0:28 offset1:29
	v_mul_f32_e32 v82, v62, v81
	v_mul_f32_e32 v83, v63, v81
	ds_write2st64_b32 v80, v82, v83 offset0:30 offset1:31
	v_mul_f32_e32 v82, v32, v81
	v_mul_f32_e32 v83, v33, v81
	ds_write2st64_b32 v80, v82, v83 offset0:32 offset1:33
	v_mul_f32_e32 v82, v34, v81
	v_mul_f32_e32 v83, v35, v81
	ds_write2st64_b32 v80, v82, v83 offset0:34 offset1:35
	v_mul_f32_e32 v82, v36, v81
	v_mul_f32_e32 v83, v37, v81
	ds_write2st64_b32 v80, v82, v83 offset0:36 offset1:37
	v_mul_f32_e32 v82, v38, v81
	v_mul_f32_e32 v83, v39, v81
	ds_write2st64_b32 v80, v82, v83 offset0:38 offset1:39
	v_mul_f32_e32 v82, v40, v81
	v_mul_f32_e32 v83, v41, v81
	ds_write2st64_b32 v80, v82, v83 offset0:40 offset1:41
	v_mul_f32_e32 v82, v42, v81
	v_mul_f32_e32 v83, v43, v81
	ds_write2st64_b32 v80, v82, v83 offset0:42 offset1:43
	v_mul_f32_e32 v82, v44, v81
	v_mul_f32_e32 v83, v45, v81
	ds_write2st64_b32 v80, v82, v83 offset0:44 offset1:45
	v_mul_f32_e32 v82, v46, v81
	v_mul_f32_e32 v83, v47, v81
	ds_write2st64_b32 v80, v82, v83 offset0:46 offset1:47
	v_mul_f32_e32 v82, v16, v81
	v_mul_f32_e32 v83, v17, v81
	ds_write2st64_b32 v80, v82, v83 offset0:48 offset1:49
	v_mul_f32_e32 v82, v18, v81
	v_mul_f32_e32 v83, v19, v81
	ds_write2st64_b32 v80, v82, v83 offset0:50 offset1:51
	v_mul_f32_e32 v82, v20, v81
	v_mul_f32_e32 v83, v21, v81
	ds_write2st64_b32 v80, v82, v83 offset0:52 offset1:53
	v_mul_f32_e32 v82, v22, v81
	v_mul_f32_e32 v83, v23, v81
	ds_write2st64_b32 v80, v82, v83 offset0:54 offset1:55
	v_mul_f32_e32 v82, v24, v81
	v_mul_f32_e32 v83, v25, v81
	ds_write2st64_b32 v80, v82, v83 offset0:56 offset1:57
	v_mul_f32_e32 v82, v26, v81
	v_mul_f32_e32 v83, v27, v81
	ds_write2st64_b32 v80, v82, v83 offset0:58 offset1:59
	v_mul_f32_e32 v82, v28, v81
	v_mul_f32_e32 v83, v29, v81
	ds_write2st64_b32 v80, v82, v83 offset0:60 offset1:61
	v_mul_f32_e32 v82, v30, v81
	v_mul_f32_e32 v81, v31, v81
	ds_write2st64_b32 v80, v82, v81 offset0:62 offset1:63
